# V-transposed scatter stores packed four tokens per lane (DPP xor-1 and xor-2 exchange): 128/64 two-byte stores become 32/16 dwordx2 stores
# baseline (speedup 1.0000x reference)
; __device__ __forceinline__ float rstd4(const float* pp, int row, float invn) { const f32x4 a = *(const f32x4*)(pp + (size_t)row * 4); return rsqrtf(((a.x + a.y) + (a.z + a.w)) * invn + 1e-6f); }
.LBB0_1097:
	v_mbcnt_lo_u32_b32 v237, -1, 0
	v_mbcnt_hi_u32_b32 v237, -1, v237
	v_bfe_u32 v239, v237, 1, 1
	v_and_b32_e32 v238, 3, v237
	v_mul_u32_u24_e32 v232, 0xffe, v238
	v_and_b32_e32 v237, 1, v237
	v_mov_b32_e32 v233, 0
	v_mov_b32_e32 v234, 0x4000
	v_mov_b32_e32 v235, 0
	v_mov_b32_e32 v236, 0x7060302
	v_mov_b32_e32 v238, 0x3020706
	v_cmp_ne_u32_e32 vcc, 0, v237
	s_nop 1
	v_cndmask_b32_e32 v236, v236, v238, vcc
	s_lshl_b32 s33, s45, 8
	s_add_i32 s33, s33, s92
	s_ashr_i32 s4, s33, 8
	s_lshl_b32 s50, s44, 1
	v_or_b32_e32 v154, s33, v137
	s_and_b32 s14, s4, -8
	v_readlane_b32 s4, v254, 12
	v_ashrrev_i32_e32 v155, 31, v154
	v_readlane_b32 s5, v254, 13
	s_nop 1
	v_lshl_add_u64 v[156:157], v[154:155], 4, s[4:5]
	v_mov_b32_e32 v218, v154
	v_ashrrev_i32_e32 v219, 31, v218
	v_lshl_add_u64 v[218:219], v[218:219], 4, s[4:5]
	global_load_dwordx4 v[186:189], v[218:219], off
	v_add_u32_e32 v218, 16, v154
	v_ashrrev_i32_e32 v219, 31, v218
	v_lshl_add_u64 v[218:219], v[218:219], 4, s[4:5]
	global_load_dwordx4 v[190:193], v[218:219], off
	v_add_u32_e32 v218, 32, v154
	v_ashrrev_i32_e32 v219, 31, v218
	v_lshl_add_u64 v[218:219], v[218:219], 4, s[4:5]
	global_load_dwordx4 v[194:197], v[218:219], off
	v_add_u32_e32 v218, 48, v154
	v_ashrrev_i32_e32 v219, 31, v218
	v_lshl_add_u64 v[218:219], v[218:219], 4, s[4:5]
	global_load_dwordx4 v[198:201], v[218:219], off
	v_add_u32_e32 v218, 128, v154
	v_ashrrev_i32_e32 v219, 31, v218
	v_lshl_add_u64 v[218:219], v[218:219], 4, s[4:5]
	global_load_dwordx4 v[202:205], v[218:219], off
	v_add_u32_e32 v218, 144, v154
	v_ashrrev_i32_e32 v219, 31, v218
	v_lshl_add_u64 v[218:219], v[218:219], 4, s[4:5]
	global_load_dwordx4 v[206:209], v[218:219], off
	v_add_u32_e32 v218, 160, v154
	v_ashrrev_i32_e32 v219, 31, v218
	v_lshl_add_u64 v[218:219], v[218:219], 4, s[4:5]
	global_load_dwordx4 v[210:213], v[218:219], off
	v_add_u32_e32 v218, 176, v154
	v_ashrrev_i32_e32 v219, 31, v218
	v_lshl_add_u64 v[218:219], v[218:219], 4, s[4:5]
	global_load_dwordx4 v[214:217], v[218:219], off
	s_waitcnt vmcnt(0)
	s_mov_b32 s4, 0x800000
	v_mov_b32_e32 v156, v186
	v_mov_b32_e32 v157, v187
	v_mov_b32_e32 v158, v188
	v_mov_b32_e32 v159, v189
	v_mov_b32_e32 v160, v157
	v_mov_b32_e32 v161, v158
	v_mov_b32_e32 v157, v159
	v_pk_add_f32 v[156:157], v[160:161], v[156:157]
	s_nop 0
	v_add_f32_e32 v144, v156, v157
	v_fmamk_f32 v144, v144, 0x3c000000, v171
	v_cmp_gt_f32_e32 vcc, s4, v144
	v_mul_f32_e32 v155, 0x4b800000, v144
	s_mov_b64 s[4:5], -1
	v_cndmask_b32_e32 v144, v144, v155, vcc
	v_rsq_f32_e32 v144, v144
	s_nop 0
	v_mul_f32_e32 v155, 0x45800000, v144
	v_cndmask_b32_e32 v156, v144, v155, vcc
	v_bitop3_b32 v144, s33, v178, v137 bitop3:0xc8
	v_pk_mul_f32 v[122:123], v[122:123], v[156:157] op_sel_hi:[1,0]
	v_pk_mul_f32 v[158:159], v[120:121], v[156:157] op_sel_hi:[1,0]
	v_pk_mul_f32 v[120:121], v[126:127], v[156:157] op_sel_hi:[1,0]
	v_pk_mul_f32 v[124:125], v[124:125], v[156:157] op_sel_hi:[1,0]
	s_and_b64 vcc, exec, s[24:25]
	v_lshlrev_b32_e32 v126, 1, v144
	s_cbranch_vccz .LBB0_1099
	s_add_i32 s4, s14, s50
	s_ashr_i32 s5, s4, 31
	s_lshl_b64 s[4:5], s[4:5], 18
	v_lshl_add_u64 v[160:161], v[138:139], 0, s[4:5]
	v_mov_b32_e32 v127, v145
	v_lshl_add_u64 v[160:161], v[160:161], 0, v[126:127]
	s_movk_i32 s4, 0x2000
	s_movk_i32 s4, 0x3000
	s_movk_i32 s4, 0x4000
	v_cmp_ne_u32_e32 vcc, 0, v237
	v_bfe_u32 v238, v158, 16, 1
	v_add3_u32 v158, v158, v238, s1
	v_bfe_u32 v238, v159, 16, 1
	v_add3_u32 v159, v159, v238, s1
	v_bfe_u32 v238, v122, 16, 1
	v_add3_u32 v122, v122, v238, s1
	v_bfe_u32 v238, v123, 16, 1
	v_add3_u32 v123, v123, v238, s1
	v_bfe_u32 v238, v124, 16, 1
	v_add3_u32 v124, v124, v238, s1
	v_bfe_u32 v238, v125, 16, 1
	v_add3_u32 v125, v125, v238, s1
	v_bfe_u32 v238, v120, 16, 1
	v_add3_u32 v120, v120, v238, s1
	v_bfe_u32 v238, v121, 16, 1
	v_add3_u32 v121, v121, v238, s1
	v_cndmask_b32_e32 v220, v158, v159, vcc
	v_cndmask_b32_e32 v224, v159, v158, vcc
	v_cndmask_b32_e32 v221, v122, v123, vcc
	v_cndmask_b32_e32 v225, v123, v122, vcc
	v_cndmask_b32_e32 v222, v124, v125, vcc
	v_cndmask_b32_e32 v226, v125, v124, vcc
	v_cndmask_b32_e32 v223, v120, v121, vcc
	v_cndmask_b32_e32 v227, v121, v120, vcc
	v_lshl_add_u64 v[228:229], v[160:161], 0, v[232:233]
	v_mov_b32_dpp v224, v224 quad_perm:[1,0,3,2] row_mask:0xf bank_mask:0xf
	v_mov_b32_dpp v225, v225 quad_perm:[1,0,3,2] row_mask:0xf bank_mask:0xf
	v_mov_b32_dpp v226, v226 quad_perm:[1,0,3,2] row_mask:0xf bank_mask:0xf
	v_mov_b32_dpp v227, v227 quad_perm:[1,0,3,2] row_mask:0xf bank_mask:0xf
	s_nop 0
	v_perm_b32 v220, v224, v220, v236
	v_perm_b32 v221, v225, v221, v236
	v_perm_b32 v222, v226, v222, v236
	v_perm_b32 v223, v227, v223, v236
	v_cmp_ne_u32_e32 vcc, 0, v239
	s_nop 1
	v_cndmask_b32_e32 v224, v221, v220, vcc
	v_cndmask_b32_e32 v225, v223, v222, vcc
	s_nop 0
	v_mov_b32_dpp v224, v224 quad_perm:[2,3,0,1] row_mask:0xf bank_mask:0xf
	v_mov_b32_dpp v225, v225 quad_perm:[2,3,0,1] row_mask:0xf bank_mask:0xf
	s_nop 0
	v_cndmask_b32_e32 v220, v220, v224, vcc
	v_cndmask_b32_e32 v221, v224, v221, vcc
	v_cndmask_b32_e32 v222, v222, v225, vcc
	v_cndmask_b32_e32 v223, v225, v223, vcc
	global_store_dwordx2 v[228:229], v[220:221], off
	v_lshl_add_u64 v[228:229], v[228:229], 0, v[234:235]
	global_store_dwordx2 v[228:229], v[222:223], off
	s_mov_b64 s[4:5], 0

.LBB0_1101:
	v_mov_b32_e32 v120, v156
	v_mov_b32_e32 v121, v156
	v_mov_b32_e32 v157, v156
	v_pk_mul_f32 v[118:119], v[118:119], v[120:121]
	v_pk_mul_f32 v[114:115], v[114:115], v[120:121]
	v_cndmask_b32_e64 v120, 0, 1, s[24:25]
	s_or_b32 s51, s50, 1
	v_pk_mul_f32 v[116:117], v[116:117], v[156:157]
	v_pk_mul_f32 v[112:113], v[112:113], v[156:157]
	v_cmp_ne_u32_e64 s[4:5], 1, v120
	s_andn2_b64 vcc, exec, s[24:25]
	s_mov_b64 s[34:35], -1
	s_cbranch_vccnz .LBB0_1103
	s_add_i32 s34, s14, s51
	s_ashr_i32 s35, s34, 31
	s_lshl_b64 s[34:35], s[34:35], 18
	v_lshl_add_u64 v[120:121], v[138:139], 0, s[34:35]
	v_mov_b32_e32 v127, v145
	v_lshl_add_u64 v[120:121], v[120:121], 0, v[126:127]
	s_movk_i32 s15, 0x1000
	s_movk_i32 s15, 0x2000
	s_movk_i32 s15, 0x3000
	s_movk_i32 s15, 0x4000
	s_mov_b64 s[34:35], 0
	v_cmp_ne_u32_e32 vcc, 0, v237
	v_bfe_u32 v238, v116, 16, 1
	v_add3_u32 v116, v116, v238, s1
	v_bfe_u32 v238, v117, 16, 1
	v_add3_u32 v117, v117, v238, s1
	v_bfe_u32 v238, v118, 16, 1
	v_add3_u32 v118, v118, v238, s1
	v_bfe_u32 v238, v119, 16, 1
	v_add3_u32 v119, v119, v238, s1
	v_bfe_u32 v238, v112, 16, 1
	v_add3_u32 v112, v112, v238, s1
	v_bfe_u32 v238, v113, 16, 1
	v_add3_u32 v113, v113, v238, s1
	v_bfe_u32 v238, v114, 16, 1
	v_add3_u32 v114, v114, v238, s1
	v_bfe_u32 v238, v115, 16, 1
	v_add3_u32 v115, v115, v238, s1
	v_cndmask_b32_e32 v220, v116, v117, vcc
	v_cndmask_b32_e32 v224, v117, v116, vcc
	v_cndmask_b32_e32 v221, v118, v119, vcc
	v_cndmask_b32_e32 v225, v119, v118, vcc
	v_cndmask_b32_e32 v222, v112, v113, vcc
	v_cndmask_b32_e32 v226, v113, v112, vcc
	v_cndmask_b32_e32 v223, v114, v115, vcc
	v_cndmask_b32_e32 v227, v115, v114, vcc
	v_lshl_add_u64 v[228:229], v[120:121], 0, v[232:233]
	v_mov_b32_dpp v224, v224 quad_perm:[1,0,3,2] row_mask:0xf bank_mask:0xf
	v_mov_b32_dpp v225, v225 quad_perm:[1,0,3,2] row_mask:0xf bank_mask:0xf
	v_mov_b32_dpp v226, v226 quad_perm:[1,0,3,2] row_mask:0xf bank_mask:0xf
	v_mov_b32_dpp v227, v227 quad_perm:[1,0,3,2] row_mask:0xf bank_mask:0xf
	s_nop 0
	v_perm_b32 v220, v224, v220, v236
	v_perm_b32 v221, v225, v221, v236
	v_perm_b32 v222, v226, v222, v236
	v_perm_b32 v223, v227, v223, v236
	v_cmp_ne_u32_e32 vcc, 0, v239
	s_nop 1
	v_cndmask_b32_e32 v224, v221, v220, vcc
	v_cndmask_b32_e32 v225, v223, v222, vcc
	s_nop 0
	v_mov_b32_dpp v224, v224 quad_perm:[2,3,0,1] row_mask:0xf bank_mask:0xf
	v_mov_b32_dpp v225, v225 quad_perm:[2,3,0,1] row_mask:0xf bank_mask:0xf
	s_nop 0
	v_cndmask_b32_e32 v220, v220, v224, vcc
	v_cndmask_b32_e32 v221, v224, v221, vcc
	v_cndmask_b32_e32 v222, v222, v225, vcc
	v_cndmask_b32_e32 v223, v225, v223, vcc
	global_store_dwordx2 v[228:229], v[220:221], off
	v_lshl_add_u64 v[228:229], v[228:229], 0, v[234:235]
	global_store_dwordx2 v[228:229], v[222:223], off

; __device__ __forceinline__ float rstd4(const float* pp, int row, float invn) { const f32x4 a = *(const f32x4*)(pp + (size_t)row * 4); return rsqrtf(((a.x + a.y) + (a.z + a.w)) * invn + 1e-6f); }
.LBB0_1105:
	v_or_b32_e32 v114, 16, v154
	v_readlane_b32 s44, v254, 12
	v_ashrrev_i32_e32 v115, 31, v114
	v_readlane_b32 s45, v254, 13
	s_mov_b32 s15, 0x800000
	s_nop 0
	v_lshl_add_u64 v[112:113], v[114:115], 4, s[44:45]
	s_mov_b64 s[44:45], -1
	v_mov_b32_e32 v116, v190
	v_mov_b32_e32 v117, v191
	v_mov_b32_e32 v118, v192
	v_mov_b32_e32 v119, v193
	v_mov_b32_e32 v112, v117
	v_mov_b32_e32 v113, v118
	v_mov_b32_e32 v117, v119
	v_pk_add_f32 v[112:113], v[112:113], v[116:117]
	s_nop 0
	v_add_f32_e32 v112, v112, v113
	v_fmamk_f32 v112, v112, 0x3c000000, v171
	v_cmp_gt_f32_e32 vcc, s15, v112
	v_mul_f32_e32 v113, 0x4b800000, v112
	s_movk_i32 s15, 0x7df
	v_cndmask_b32_e32 v112, v112, v113, vcc
	v_rsq_f32_e32 v112, v112
	s_nop 0
	v_mul_f32_e32 v113, 0x45800000, v112
	v_cndmask_b32_e32 v112, v112, v113, vcc
	v_bitop3_b32 v113, v154, s15, 16 bitop3:0xc8
	v_pk_mul_f32 v[110:111], v[110:111], v[112:113] op_sel_hi:[1,0]
	v_pk_mul_f32 v[108:109], v[108:109], v[112:113] op_sel_hi:[1,0]
	v_pk_mul_f32 v[106:107], v[106:107], v[112:113] op_sel_hi:[1,0]
	v_pk_mul_f32 v[104:105], v[104:105], v[112:113] op_sel_hi:[1,0]
	s_and_b64 vcc, exec, s[4:5]
	v_lshlrev_b32_e32 v116, 1, v113
	s_cbranch_vccnz .LBB0_1107
	s_add_i32 s44, s14, s50
	s_ashr_i32 s45, s44, 31
	s_lshl_b64 s[44:45], s[44:45], 18
	v_lshl_add_u64 v[118:119], v[138:139], 0, s[44:45]
	v_mov_b32_e32 v117, v145
	v_lshl_add_u64 v[118:119], v[118:119], 0, v[116:117]
	s_movk_i32 s15, 0x1000
	s_movk_i32 s15, 0x2000
	s_movk_i32 s15, 0x3000
	s_movk_i32 s15, 0x4000
	s_mov_b64 s[44:45], 0
	v_cmp_ne_u32_e32 vcc, 0, v237
	v_bfe_u32 v238, v108, 16, 1
	v_add3_u32 v108, v108, v238, s1
	v_bfe_u32 v238, v109, 16, 1
	v_add3_u32 v109, v109, v238, s1
	v_bfe_u32 v238, v110, 16, 1
	v_add3_u32 v110, v110, v238, s1
	v_bfe_u32 v238, v111, 16, 1
	v_add3_u32 v111, v111, v238, s1
	v_bfe_u32 v238, v104, 16, 1
	v_add3_u32 v104, v104, v238, s1
	v_bfe_u32 v238, v105, 16, 1
	v_add3_u32 v105, v105, v238, s1
	v_bfe_u32 v238, v106, 16, 1
	v_add3_u32 v106, v106, v238, s1
	v_bfe_u32 v238, v107, 16, 1
	v_add3_u32 v107, v107, v238, s1
	v_cndmask_b32_e32 v220, v108, v109, vcc
	v_cndmask_b32_e32 v224, v109, v108, vcc
	v_cndmask_b32_e32 v221, v110, v111, vcc
	v_cndmask_b32_e32 v225, v111, v110, vcc
	v_cndmask_b32_e32 v222, v104, v105, vcc
	v_cndmask_b32_e32 v226, v105, v104, vcc
	v_cndmask_b32_e32 v223, v106, v107, vcc
	v_cndmask_b32_e32 v227, v107, v106, vcc
	v_lshl_add_u64 v[228:229], v[118:119], 0, v[232:233]
	v_mov_b32_dpp v224, v224 quad_perm:[1,0,3,2] row_mask:0xf bank_mask:0xf
	v_mov_b32_dpp v225, v225 quad_perm:[1,0,3,2] row_mask:0xf bank_mask:0xf
	v_mov_b32_dpp v226, v226 quad_perm:[1,0,3,2] row_mask:0xf bank_mask:0xf
	v_mov_b32_dpp v227, v227 quad_perm:[1,0,3,2] row_mask:0xf bank_mask:0xf
	s_nop 0
	v_perm_b32 v220, v224, v220, v236
	v_perm_b32 v221, v225, v221, v236
	v_perm_b32 v222, v226, v222, v236
	v_perm_b32 v223, v227, v223, v236
	v_cmp_ne_u32_e32 vcc, 0, v239
	s_nop 1
	v_cndmask_b32_e32 v224, v221, v220, vcc
	v_cndmask_b32_e32 v225, v223, v222, vcc
	s_nop 0
	v_mov_b32_dpp v224, v224 quad_perm:[2,3,0,1] row_mask:0xf bank_mask:0xf
	v_mov_b32_dpp v225, v225 quad_perm:[2,3,0,1] row_mask:0xf bank_mask:0xf
	s_nop 0
	v_cndmask_b32_e32 v220, v220, v224, vcc
	v_cndmask_b32_e32 v221, v224, v221, vcc
	v_cndmask_b32_e32 v222, v222, v225, vcc
	v_cndmask_b32_e32 v223, v225, v223, vcc
	global_store_dwordx2 v[228:229], v[220:221], off
	v_lshl_add_u64 v[228:229], v[228:229], 0, v[234:235]
	global_store_dwordx2 v[228:229], v[222:223], off

.LBB0_1109:
	v_mov_b32_e32 v113, v112
	v_mov_b32_e32 v104, v112
	v_mov_b32_e32 v105, v112
	v_pk_mul_f32 v[102:103], v[102:103], v[104:105]
	v_pk_mul_f32 v[100:101], v[100:101], v[112:113]
	v_pk_mul_f32 v[98:99], v[98:99], v[104:105]
	v_pk_mul_f32 v[96:97], v[96:97], v[112:113]
	s_and_b64 vcc, exec, s[4:5]
	s_mov_b64 s[44:45], -1
	s_cbranch_vccnz .LBB0_1111
	s_add_i32 s44, s14, s51
	s_ashr_i32 s45, s44, 31
	s_lshl_b64 s[44:45], s[44:45], 18
	v_lshl_add_u64 v[104:105], v[138:139], 0, s[44:45]
	v_mov_b32_e32 v117, v145
	v_lshl_add_u64 v[104:105], v[104:105], 0, v[116:117]
	s_movk_i32 s15, 0x1000
	s_movk_i32 s15, 0x2000
	s_movk_i32 s15, 0x3000
	s_movk_i32 s15, 0x4000
	s_mov_b64 s[44:45], 0
	v_cmp_ne_u32_e32 vcc, 0, v237
	v_bfe_u32 v238, v100, 16, 1
	v_add3_u32 v100, v100, v238, s1
	v_bfe_u32 v238, v101, 16, 1
	v_add3_u32 v101, v101, v238, s1
	v_bfe_u32 v238, v102, 16, 1
	v_add3_u32 v102, v102, v238, s1
	v_bfe_u32 v238, v103, 16, 1
	v_add3_u32 v103, v103, v238, s1
	v_bfe_u32 v238, v96, 16, 1
	v_add3_u32 v96, v96, v238, s1
	v_bfe_u32 v238, v97, 16, 1
	v_add3_u32 v97, v97, v238, s1
	v_bfe_u32 v238, v98, 16, 1
	v_add3_u32 v98, v98, v238, s1
	v_bfe_u32 v238, v99, 16, 1
	v_add3_u32 v99, v99, v238, s1
	v_cndmask_b32_e32 v220, v100, v101, vcc
	v_cndmask_b32_e32 v224, v101, v100, vcc
	v_cndmask_b32_e32 v221, v102, v103, vcc
	v_cndmask_b32_e32 v225, v103, v102, vcc
	v_cndmask_b32_e32 v222, v96, v97, vcc
	v_cndmask_b32_e32 v226, v97, v96, vcc
	v_cndmask_b32_e32 v223, v98, v99, vcc
	v_cndmask_b32_e32 v227, v99, v98, vcc
	v_lshl_add_u64 v[228:229], v[104:105], 0, v[232:233]
	v_mov_b32_dpp v224, v224 quad_perm:[1,0,3,2] row_mask:0xf bank_mask:0xf
	v_mov_b32_dpp v225, v225 quad_perm:[1,0,3,2] row_mask:0xf bank_mask:0xf
	v_mov_b32_dpp v226, v226 quad_perm:[1,0,3,2] row_mask:0xf bank_mask:0xf
	v_mov_b32_dpp v227, v227 quad_perm:[1,0,3,2] row_mask:0xf bank_mask:0xf
	s_nop 0
	v_perm_b32 v220, v224, v220, v236
	v_perm_b32 v221, v225, v221, v236
	v_perm_b32 v222, v226, v222, v236
	v_perm_b32 v223, v227, v223, v236
	v_cmp_ne_u32_e32 vcc, 0, v239
	s_nop 1
	v_cndmask_b32_e32 v224, v221, v220, vcc
	v_cndmask_b32_e32 v225, v223, v222, vcc
	s_nop 0
	v_mov_b32_dpp v224, v224 quad_perm:[2,3,0,1] row_mask:0xf bank_mask:0xf
	v_mov_b32_dpp v225, v225 quad_perm:[2,3,0,1] row_mask:0xf bank_mask:0xf
	s_nop 0
	v_cndmask_b32_e32 v220, v220, v224, vcc
	v_cndmask_b32_e32 v221, v224, v221, vcc
	v_cndmask_b32_e32 v222, v222, v225, vcc
	v_cndmask_b32_e32 v223, v225, v223, vcc
	global_store_dwordx2 v[228:229], v[220:221], off
	v_lshl_add_u64 v[228:229], v[228:229], 0, v[234:235]
	global_store_dwordx2 v[228:229], v[222:223], off

; __device__ __forceinline__ float rstd4(const float* pp, int row, float invn) { const f32x4 a = *(const f32x4*)(pp + (size_t)row * 4); return rsqrtf(((a.x + a.y) + (a.z + a.w)) * invn + 1e-6f); }
.LBB0_1113:
	v_or_b32_e32 v98, 32, v154
	v_readlane_b32 s44, v254, 12
	v_ashrrev_i32_e32 v99, 31, v98
	v_readlane_b32 s45, v254, 13
	s_mov_b32 s15, 0x800000
	s_nop 0
	v_lshl_add_u64 v[96:97], v[98:99], 4, s[44:45]
	s_mov_b64 s[44:45], -1
	v_mov_b32_e32 v100, v194
	v_mov_b32_e32 v101, v195
	v_mov_b32_e32 v102, v196
	v_mov_b32_e32 v103, v197
	v_mov_b32_e32 v96, v101
	v_mov_b32_e32 v97, v102
	v_mov_b32_e32 v101, v103
	v_pk_add_f32 v[96:97], v[96:97], v[100:101]
	s_nop 0
	v_add_f32_e32 v96, v96, v97
	v_fmamk_f32 v96, v96, 0x3c000000, v171
	v_cmp_gt_f32_e32 vcc, s15, v96
	v_mul_f32_e32 v97, 0x4b800000, v96
	s_movk_i32 s15, 0x7ef
	v_cndmask_b32_e32 v96, v96, v97, vcc
	v_rsq_f32_e32 v96, v96
	s_nop 0
	v_mul_f32_e32 v97, 0x45800000, v96
	v_cndmask_b32_e32 v96, v96, v97, vcc
	v_bitop3_b32 v97, v154, s15, 32 bitop3:0xc8
	v_pk_mul_f32 v[94:95], v[94:95], v[96:97] op_sel_hi:[1,0]
	v_pk_mul_f32 v[92:93], v[92:93], v[96:97] op_sel_hi:[1,0]
	v_pk_mul_f32 v[90:91], v[90:91], v[96:97] op_sel_hi:[1,0]
	v_pk_mul_f32 v[88:89], v[88:89], v[96:97] op_sel_hi:[1,0]
	s_and_b64 vcc, exec, s[4:5]
	v_lshlrev_b32_e32 v100, 1, v97
	s_cbranch_vccnz .LBB0_1115
	s_add_i32 s44, s14, s50
	s_ashr_i32 s45, s44, 31
	s_lshl_b64 s[44:45], s[44:45], 18
	v_lshl_add_u64 v[102:103], v[138:139], 0, s[44:45]
	v_mov_b32_e32 v101, v145
	v_lshl_add_u64 v[102:103], v[102:103], 0, v[100:101]
	s_movk_i32 s15, 0x1000
	s_movk_i32 s15, 0x2000
	s_movk_i32 s15, 0x3000
	s_movk_i32 s15, 0x4000
	s_mov_b64 s[44:45], 0
	v_cmp_ne_u32_e32 vcc, 0, v237
	v_bfe_u32 v238, v92, 16, 1
	v_add3_u32 v92, v92, v238, s1
	v_bfe_u32 v238, v93, 16, 1
	v_add3_u32 v93, v93, v238, s1
	v_bfe_u32 v238, v94, 16, 1
	v_add3_u32 v94, v94, v238, s1
	v_bfe_u32 v238, v95, 16, 1
	v_add3_u32 v95, v95, v238, s1
	v_bfe_u32 v238, v88, 16, 1
	v_add3_u32 v88, v88, v238, s1
	v_bfe_u32 v238, v89, 16, 1
	v_add3_u32 v89, v89, v238, s1
	v_bfe_u32 v238, v90, 16, 1
	v_add3_u32 v90, v90, v238, s1
	v_bfe_u32 v238, v91, 16, 1
	v_add3_u32 v91, v91, v238, s1
	v_cndmask_b32_e32 v220, v92, v93, vcc
	v_cndmask_b32_e32 v224, v93, v92, vcc
	v_cndmask_b32_e32 v221, v94, v95, vcc
	v_cndmask_b32_e32 v225, v95, v94, vcc
	v_cndmask_b32_e32 v222, v88, v89, vcc
	v_cndmask_b32_e32 v226, v89, v88, vcc
	v_cndmask_b32_e32 v223, v90, v91, vcc
	v_cndmask_b32_e32 v227, v91, v90, vcc
	v_lshl_add_u64 v[228:229], v[102:103], 0, v[232:233]
	v_mov_b32_dpp v224, v224 quad_perm:[1,0,3,2] row_mask:0xf bank_mask:0xf
	v_mov_b32_dpp v225, v225 quad_perm:[1,0,3,2] row_mask:0xf bank_mask:0xf
	v_mov_b32_dpp v226, v226 quad_perm:[1,0,3,2] row_mask:0xf bank_mask:0xf
	v_mov_b32_dpp v227, v227 quad_perm:[1,0,3,2] row_mask:0xf bank_mask:0xf
	s_nop 0
	v_perm_b32 v220, v224, v220, v236
	v_perm_b32 v221, v225, v221, v236
	v_perm_b32 v222, v226, v222, v236
	v_perm_b32 v223, v227, v223, v236
	v_cmp_ne_u32_e32 vcc, 0, v239
	s_nop 1
	v_cndmask_b32_e32 v224, v221, v220, vcc
	v_cndmask_b32_e32 v225, v223, v222, vcc
	s_nop 0
	v_mov_b32_dpp v224, v224 quad_perm:[2,3,0,1] row_mask:0xf bank_mask:0xf
	v_mov_b32_dpp v225, v225 quad_perm:[2,3,0,1] row_mask:0xf bank_mask:0xf
	s_nop 0
	v_cndmask_b32_e32 v220, v220, v224, vcc
	v_cndmask_b32_e32 v221, v224, v221, vcc
	v_cndmask_b32_e32 v222, v222, v225, vcc
	v_cndmask_b32_e32 v223, v225, v223, vcc
	global_store_dwordx2 v[228:229], v[220:221], off
	v_lshl_add_u64 v[228:229], v[228:229], 0, v[234:235]
	global_store_dwordx2 v[228:229], v[222:223], off

.LBB0_1117:
	v_mov_b32_e32 v97, v96
	v_mov_b32_e32 v88, v96
	v_mov_b32_e32 v89, v96
	v_pk_mul_f32 v[86:87], v[86:87], v[88:89]
	v_pk_mul_f32 v[84:85], v[84:85], v[96:97]
	v_pk_mul_f32 v[82:83], v[82:83], v[88:89]
	v_pk_mul_f32 v[80:81], v[80:81], v[96:97]
	s_and_b64 vcc, exec, s[4:5]
	s_mov_b64 s[44:45], -1
	s_cbranch_vccnz .LBB0_1119
	s_add_i32 s44, s14, s51
	s_ashr_i32 s45, s44, 31
	s_lshl_b64 s[44:45], s[44:45], 18
	v_lshl_add_u64 v[88:89], v[138:139], 0, s[44:45]
	v_mov_b32_e32 v101, v145
	v_lshl_add_u64 v[88:89], v[88:89], 0, v[100:101]
	s_movk_i32 s15, 0x1000
	s_movk_i32 s15, 0x2000
	s_movk_i32 s15, 0x3000
	s_movk_i32 s15, 0x4000
	s_mov_b64 s[44:45], 0
	v_cmp_ne_u32_e32 vcc, 0, v237
	v_bfe_u32 v238, v84, 16, 1
	v_add3_u32 v84, v84, v238, s1
	v_bfe_u32 v238, v85, 16, 1
	v_add3_u32 v85, v85, v238, s1
	v_bfe_u32 v238, v86, 16, 1
	v_add3_u32 v86, v86, v238, s1
	v_bfe_u32 v238, v87, 16, 1
	v_add3_u32 v87, v87, v238, s1
	v_bfe_u32 v238, v80, 16, 1
	v_add3_u32 v80, v80, v238, s1
	v_bfe_u32 v238, v81, 16, 1
	v_add3_u32 v81, v81, v238, s1
	v_bfe_u32 v238, v82, 16, 1
	v_add3_u32 v82, v82, v238, s1
	v_bfe_u32 v238, v83, 16, 1
	v_add3_u32 v83, v83, v238, s1
	v_cndmask_b32_e32 v220, v84, v85, vcc
	v_cndmask_b32_e32 v224, v85, v84, vcc
	v_cndmask_b32_e32 v221, v86, v87, vcc
	v_cndmask_b32_e32 v225, v87, v86, vcc
	v_cndmask_b32_e32 v222, v80, v81, vcc
	v_cndmask_b32_e32 v226, v81, v80, vcc
	v_cndmask_b32_e32 v223, v82, v83, vcc
	v_cndmask_b32_e32 v227, v83, v82, vcc
	v_lshl_add_u64 v[228:229], v[88:89], 0, v[232:233]
	v_mov_b32_dpp v224, v224 quad_perm:[1,0,3,2] row_mask:0xf bank_mask:0xf
	v_mov_b32_dpp v225, v225 quad_perm:[1,0,3,2] row_mask:0xf bank_mask:0xf
	v_mov_b32_dpp v226, v226 quad_perm:[1,0,3,2] row_mask:0xf bank_mask:0xf
	v_mov_b32_dpp v227, v227 quad_perm:[1,0,3,2] row_mask:0xf bank_mask:0xf
	s_nop 0
	v_perm_b32 v220, v224, v220, v236
	v_perm_b32 v221, v225, v221, v236
	v_perm_b32 v222, v226, v222, v236
	v_perm_b32 v223, v227, v223, v236
	v_cmp_ne_u32_e32 vcc, 0, v239
	s_nop 1
	v_cndmask_b32_e32 v224, v221, v220, vcc
	v_cndmask_b32_e32 v225, v223, v222, vcc
	s_nop 0
	v_mov_b32_dpp v224, v224 quad_perm:[2,3,0,1] row_mask:0xf bank_mask:0xf
	v_mov_b32_dpp v225, v225 quad_perm:[2,3,0,1] row_mask:0xf bank_mask:0xf
	s_nop 0
	v_cndmask_b32_e32 v220, v220, v224, vcc
	v_cndmask_b32_e32 v221, v224, v221, vcc
	v_cndmask_b32_e32 v222, v222, v225, vcc
	v_cndmask_b32_e32 v223, v225, v223, vcc
	global_store_dwordx2 v[228:229], v[220:221], off
	v_lshl_add_u64 v[228:229], v[228:229], 0, v[234:235]
	global_store_dwordx2 v[228:229], v[222:223], off

; __device__ __forceinline__ float rstd4(const float* pp, int row, float invn) { const f32x4 a = *(const f32x4*)(pp + (size_t)row * 4); return rsqrtf(((a.x + a.y) + (a.z + a.w)) * invn + 1e-6f); }
.LBB0_1121:
	v_or_b32_e32 v82, 48, v154
	v_readlane_b32 s44, v254, 12
	v_ashrrev_i32_e32 v83, 31, v82
	v_readlane_b32 s45, v254, 13
	s_mov_b32 s15, 0x800000
	s_nop 0
	v_lshl_add_u64 v[80:81], v[82:83], 4, s[44:45]
	s_mov_b64 s[44:45], -1
	v_mov_b32_e32 v84, v198
	v_mov_b32_e32 v85, v199
	v_mov_b32_e32 v86, v200
	v_mov_b32_e32 v87, v201
	v_mov_b32_e32 v80, v85
	v_mov_b32_e32 v81, v86
	v_mov_b32_e32 v85, v87
	v_pk_add_f32 v[80:81], v[80:81], v[84:85]
	s_nop 0
	v_add_f32_e32 v80, v80, v81
	v_fmamk_f32 v80, v80, 0x3c000000, v171
	v_cmp_gt_f32_e32 vcc, s15, v80
	v_mul_f32_e32 v81, 0x4b800000, v80
	s_movk_i32 s15, 0x7ff
	v_cndmask_b32_e32 v80, v80, v81, vcc
	v_rsq_f32_e32 v80, v80
	s_nop 0
	v_mul_f32_e32 v81, 0x45800000, v80
	v_cndmask_b32_e32 v80, v80, v81, vcc
	v_bitop3_b32 v81, v154, s15, 48 bitop3:0xc8
	v_pk_mul_f32 v[78:79], v[78:79], v[80:81] op_sel_hi:[1,0]
	v_pk_mul_f32 v[76:77], v[76:77], v[80:81] op_sel_hi:[1,0]
	v_pk_mul_f32 v[74:75], v[74:75], v[80:81] op_sel_hi:[1,0]
	v_pk_mul_f32 v[72:73], v[72:73], v[80:81] op_sel_hi:[1,0]
	s_and_b64 vcc, exec, s[4:5]
	v_lshlrev_b32_e32 v84, 1, v81
	s_cbranch_vccnz .LBB0_1123
	s_add_i32 s44, s14, s50
	s_ashr_i32 s45, s44, 31
	s_lshl_b64 s[44:45], s[44:45], 18
	v_lshl_add_u64 v[86:87], v[138:139], 0, s[44:45]
	v_mov_b32_e32 v85, v145
	v_lshl_add_u64 v[86:87], v[86:87], 0, v[84:85]
	s_movk_i32 s15, 0x1000
	s_movk_i32 s15, 0x2000
	s_movk_i32 s15, 0x3000
	s_movk_i32 s15, 0x4000
	s_mov_b64 s[44:45], 0
	v_cmp_ne_u32_e32 vcc, 0, v237
	v_bfe_u32 v238, v76, 16, 1
	v_add3_u32 v76, v76, v238, s1
	v_bfe_u32 v238, v77, 16, 1
	v_add3_u32 v77, v77, v238, s1
	v_bfe_u32 v238, v78, 16, 1
	v_add3_u32 v78, v78, v238, s1
	v_bfe_u32 v238, v79, 16, 1
	v_add3_u32 v79, v79, v238, s1
	v_bfe_u32 v238, v72, 16, 1
	v_add3_u32 v72, v72, v238, s1
	v_bfe_u32 v238, v73, 16, 1
	v_add3_u32 v73, v73, v238, s1
	v_bfe_u32 v238, v74, 16, 1
	v_add3_u32 v74, v74, v238, s1
	v_bfe_u32 v238, v75, 16, 1
	v_add3_u32 v75, v75, v238, s1
	v_cndmask_b32_e32 v220, v76, v77, vcc
	v_cndmask_b32_e32 v224, v77, v76, vcc
	v_cndmask_b32_e32 v221, v78, v79, vcc
	v_cndmask_b32_e32 v225, v79, v78, vcc
	v_cndmask_b32_e32 v222, v72, v73, vcc
	v_cndmask_b32_e32 v226, v73, v72, vcc
	v_cndmask_b32_e32 v223, v74, v75, vcc
	v_cndmask_b32_e32 v227, v75, v74, vcc
	v_lshl_add_u64 v[228:229], v[86:87], 0, v[232:233]
	v_mov_b32_dpp v224, v224 quad_perm:[1,0,3,2] row_mask:0xf bank_mask:0xf
	v_mov_b32_dpp v225, v225 quad_perm:[1,0,3,2] row_mask:0xf bank_mask:0xf
	v_mov_b32_dpp v226, v226 quad_perm:[1,0,3,2] row_mask:0xf bank_mask:0xf
	v_mov_b32_dpp v227, v227 quad_perm:[1,0,3,2] row_mask:0xf bank_mask:0xf
	s_nop 0
	v_perm_b32 v220, v224, v220, v236
	v_perm_b32 v221, v225, v221, v236
	v_perm_b32 v222, v226, v222, v236
	v_perm_b32 v223, v227, v223, v236
	v_cmp_ne_u32_e32 vcc, 0, v239
	s_nop 1
	v_cndmask_b32_e32 v224, v221, v220, vcc
	v_cndmask_b32_e32 v225, v223, v222, vcc
	s_nop 0
	v_mov_b32_dpp v224, v224 quad_perm:[2,3,0,1] row_mask:0xf bank_mask:0xf
	v_mov_b32_dpp v225, v225 quad_perm:[2,3,0,1] row_mask:0xf bank_mask:0xf
	s_nop 0
	v_cndmask_b32_e32 v220, v220, v224, vcc
	v_cndmask_b32_e32 v221, v224, v221, vcc
	v_cndmask_b32_e32 v222, v222, v225, vcc
	v_cndmask_b32_e32 v223, v225, v223, vcc
	global_store_dwordx2 v[228:229], v[220:221], off
	v_lshl_add_u64 v[228:229], v[228:229], 0, v[234:235]
	global_store_dwordx2 v[228:229], v[222:223], off

.LBB0_1125:
	v_mov_b32_e32 v81, v80
	v_mov_b32_e32 v72, v80
	v_mov_b32_e32 v73, v80
	v_pk_mul_f32 v[70:71], v[70:71], v[72:73]
	v_pk_mul_f32 v[68:69], v[68:69], v[80:81]
	v_pk_mul_f32 v[66:67], v[66:67], v[72:73]
	v_pk_mul_f32 v[64:65], v[64:65], v[80:81]
	s_and_b64 vcc, exec, s[4:5]
	s_mov_b64 s[44:45], -1
	s_cbranch_vccnz .LBB0_1127
	s_add_i32 s14, s14, s51
	s_ashr_i32 s15, s14, 31
	s_lshl_b64 s[14:15], s[14:15], 18
	v_lshl_add_u64 v[72:73], v[138:139], 0, s[14:15]
	v_mov_b32_e32 v85, v145
	v_lshl_add_u64 v[72:73], v[72:73], 0, v[84:85]
	s_movk_i32 s14, 0x1000
	s_movk_i32 s14, 0x2000
	s_movk_i32 s14, 0x3000
	s_movk_i32 s14, 0x4000
	s_mov_b64 s[44:45], 0
	v_cmp_ne_u32_e32 vcc, 0, v237
	v_bfe_u32 v238, v68, 16, 1
	v_add3_u32 v68, v68, v238, s1
	v_bfe_u32 v238, v69, 16, 1
	v_add3_u32 v69, v69, v238, s1
	v_bfe_u32 v238, v70, 16, 1
	v_add3_u32 v70, v70, v238, s1
	v_bfe_u32 v238, v71, 16, 1
	v_add3_u32 v71, v71, v238, s1
	v_bfe_u32 v238, v64, 16, 1
	v_add3_u32 v64, v64, v238, s1
	v_bfe_u32 v238, v65, 16, 1
	v_add3_u32 v65, v65, v238, s1
	v_bfe_u32 v238, v66, 16, 1
	v_add3_u32 v66, v66, v238, s1
	v_bfe_u32 v238, v67, 16, 1
	v_add3_u32 v67, v67, v238, s1
	v_cndmask_b32_e32 v220, v68, v69, vcc
	v_cndmask_b32_e32 v224, v69, v68, vcc
	v_cndmask_b32_e32 v221, v70, v71, vcc
	v_cndmask_b32_e32 v225, v71, v70, vcc
	v_cndmask_b32_e32 v222, v64, v65, vcc
	v_cndmask_b32_e32 v226, v65, v64, vcc
	v_cndmask_b32_e32 v223, v66, v67, vcc
	v_cndmask_b32_e32 v227, v67, v66, vcc
	v_lshl_add_u64 v[228:229], v[72:73], 0, v[232:233]
	v_mov_b32_dpp v224, v224 quad_perm:[1,0,3,2] row_mask:0xf bank_mask:0xf
	v_mov_b32_dpp v225, v225 quad_perm:[1,0,3,2] row_mask:0xf bank_mask:0xf
	v_mov_b32_dpp v226, v226 quad_perm:[1,0,3,2] row_mask:0xf bank_mask:0xf
	v_mov_b32_dpp v227, v227 quad_perm:[1,0,3,2] row_mask:0xf bank_mask:0xf
	s_nop 0
	v_perm_b32 v220, v224, v220, v236
	v_perm_b32 v221, v225, v221, v236
	v_perm_b32 v222, v226, v222, v236
	v_perm_b32 v223, v227, v223, v236
	v_cmp_ne_u32_e32 vcc, 0, v239
	s_nop 1
	v_cndmask_b32_e32 v224, v221, v220, vcc
	v_cndmask_b32_e32 v225, v223, v222, vcc
	s_nop 0
	v_mov_b32_dpp v224, v224 quad_perm:[2,3,0,1] row_mask:0xf bank_mask:0xf
	v_mov_b32_dpp v225, v225 quad_perm:[2,3,0,1] row_mask:0xf bank_mask:0xf
	s_nop 0
	v_cndmask_b32_e32 v220, v220, v224, vcc
	v_cndmask_b32_e32 v221, v224, v221, vcc
	v_cndmask_b32_e32 v222, v222, v225, vcc
	v_cndmask_b32_e32 v223, v225, v223, vcc
	global_store_dwordx2 v[228:229], v[220:221], off
	v_lshl_add_u64 v[228:229], v[228:229], 0, v[234:235]
	global_store_dwordx2 v[228:229], v[222:223], off

; __device__ __forceinline__ float rstd4(const float* pp, int row, float invn) { const f32x4 a = *(const f32x4*)(pp + (size_t)row * 4); return rsqrtf(((a.x + a.y) + (a.z + a.w)) * invn + 1e-6f); }
.LBB0_1129:
	s_addk_i32 s33, 0x80
	s_ashr_i32 s14, s33, 8
	v_or_b32_e32 v64, s33, v137
	s_and_b32 s14, s14, -8
	v_readlane_b32 s44, v254, 12
	v_ashrrev_i32_e32 v65, 31, v64
	v_readlane_b32 s45, v254, 13
	s_mov_b32 s15, 0x800000
	s_nop 0
	v_lshl_add_u64 v[66:67], v[64:65], 4, s[44:45]
	s_mov_b64 s[44:45], -1
	v_mov_b32_e32 v66, v202
	v_mov_b32_e32 v67, v203
	v_mov_b32_e32 v68, v204
	v_mov_b32_e32 v69, v205
	v_mov_b32_e32 v70, v67
	v_mov_b32_e32 v71, v68
	v_mov_b32_e32 v67, v69
	v_pk_add_f32 v[66:67], v[70:71], v[66:67]
	s_nop 0
	v_add_f32_e32 v65, v66, v67
	v_fmamk_f32 v65, v65, 0x3c000000, v171
	v_cmp_gt_f32_e32 vcc, s15, v65
	v_mul_f32_e32 v66, 0x4b800000, v65
	s_nop 0
	v_cndmask_b32_e32 v65, v65, v66, vcc
	v_rsq_f32_e32 v65, v65
	s_nop 0
	v_mul_f32_e32 v66, 0x45800000, v65
	v_cndmask_b32_e32 v66, v65, v66, vcc
	v_bitop3_b32 v65, s33, v178, v137 bitop3:0xc8
	v_pk_mul_f32 v[62:63], v[62:63], v[66:67] op_sel_hi:[1,0]
	v_pk_mul_f32 v[60:61], v[60:61], v[66:67] op_sel_hi:[1,0]
	v_pk_mul_f32 v[58:59], v[58:59], v[66:67] op_sel_hi:[1,0]
	v_pk_mul_f32 v[56:57], v[56:57], v[66:67] op_sel_hi:[1,0]
	s_and_b64 vcc, exec, s[4:5]
	v_lshlrev_b32_e32 v68, 1, v65
	s_cbranch_vccnz .LBB0_1131
	s_add_i32 s44, s14, s50
	s_ashr_i32 s45, s44, 31
	s_lshl_b64 s[44:45], s[44:45], 18
	v_lshl_add_u64 v[70:71], v[138:139], 0, s[44:45]
	v_mov_b32_e32 v69, v145
	v_lshl_add_u64 v[70:71], v[70:71], 0, v[68:69]
	s_movk_i32 s15, 0x1000
	s_movk_i32 s15, 0x2000
	s_movk_i32 s15, 0x3000
	s_movk_i32 s15, 0x4000
	s_mov_b64 s[44:45], 0
	v_cmp_ne_u32_e32 vcc, 0, v237
	v_bfe_u32 v238, v60, 16, 1
	v_add3_u32 v60, v60, v238, s1
	v_bfe_u32 v238, v61, 16, 1
	v_add3_u32 v61, v61, v238, s1
	v_bfe_u32 v238, v62, 16, 1
	v_add3_u32 v62, v62, v238, s1
	v_bfe_u32 v238, v63, 16, 1
	v_add3_u32 v63, v63, v238, s1
	v_bfe_u32 v238, v56, 16, 1
	v_add3_u32 v56, v56, v238, s1
	v_bfe_u32 v238, v57, 16, 1
	v_add3_u32 v57, v57, v238, s1
	v_bfe_u32 v238, v58, 16, 1
	v_add3_u32 v58, v58, v238, s1
	v_bfe_u32 v238, v59, 16, 1
	v_add3_u32 v59, v59, v238, s1
	v_cndmask_b32_e32 v220, v60, v61, vcc
	v_cndmask_b32_e32 v224, v61, v60, vcc
	v_cndmask_b32_e32 v221, v62, v63, vcc
	v_cndmask_b32_e32 v225, v63, v62, vcc
	v_cndmask_b32_e32 v222, v56, v57, vcc
	v_cndmask_b32_e32 v226, v57, v56, vcc
	v_cndmask_b32_e32 v223, v58, v59, vcc
	v_cndmask_b32_e32 v227, v59, v58, vcc
	v_lshl_add_u64 v[228:229], v[70:71], 0, v[232:233]
	v_mov_b32_dpp v224, v224 quad_perm:[1,0,3,2] row_mask:0xf bank_mask:0xf
	v_mov_b32_dpp v225, v225 quad_perm:[1,0,3,2] row_mask:0xf bank_mask:0xf
	v_mov_b32_dpp v226, v226 quad_perm:[1,0,3,2] row_mask:0xf bank_mask:0xf
	v_mov_b32_dpp v227, v227 quad_perm:[1,0,3,2] row_mask:0xf bank_mask:0xf
	s_nop 0
	v_perm_b32 v220, v224, v220, v236
	v_perm_b32 v221, v225, v221, v236
	v_perm_b32 v222, v226, v222, v236
	v_perm_b32 v223, v227, v223, v236
	v_cmp_ne_u32_e32 vcc, 0, v239
	s_nop 1
	v_cndmask_b32_e32 v224, v221, v220, vcc
	v_cndmask_b32_e32 v225, v223, v222, vcc
	s_nop 0
	v_mov_b32_dpp v224, v224 quad_perm:[2,3,0,1] row_mask:0xf bank_mask:0xf
	v_mov_b32_dpp v225, v225 quad_perm:[2,3,0,1] row_mask:0xf bank_mask:0xf
	s_nop 0
	v_cndmask_b32_e32 v220, v220, v224, vcc
	v_cndmask_b32_e32 v221, v224, v221, vcc
	v_cndmask_b32_e32 v222, v222, v225, vcc
	v_cndmask_b32_e32 v223, v225, v223, vcc
	global_store_dwordx2 v[228:229], v[220:221], off
	v_lshl_add_u64 v[228:229], v[228:229], 0, v[234:235]
	global_store_dwordx2 v[228:229], v[222:223], off

.LBB0_1133:
	v_mov_b32_e32 v67, v66
	v_mov_b32_e32 v56, v66
	v_mov_b32_e32 v57, v66
	v_pk_mul_f32 v[54:55], v[54:55], v[56:57]
	v_pk_mul_f32 v[52:53], v[52:53], v[66:67]
	v_pk_mul_f32 v[50:51], v[50:51], v[56:57]
	v_pk_mul_f32 v[48:49], v[48:49], v[66:67]
	s_and_b64 vcc, exec, s[4:5]
	s_mov_b64 s[44:45], -1
	s_cbranch_vccnz .LBB0_1135
	s_add_i32 s44, s14, s51
	s_ashr_i32 s45, s44, 31
	s_lshl_b64 s[44:45], s[44:45], 18
	v_lshl_add_u64 v[56:57], v[138:139], 0, s[44:45]
	v_mov_b32_e32 v69, v145
	v_lshl_add_u64 v[56:57], v[56:57], 0, v[68:69]
	s_movk_i32 s15, 0x1000
	s_movk_i32 s15, 0x2000
	s_movk_i32 s15, 0x3000
	s_movk_i32 s15, 0x4000
	s_mov_b64 s[44:45], 0
	v_cmp_ne_u32_e32 vcc, 0, v237
	v_bfe_u32 v238, v52, 16, 1
	v_add3_u32 v52, v52, v238, s1
	v_bfe_u32 v238, v53, 16, 1
	v_add3_u32 v53, v53, v238, s1
	v_bfe_u32 v238, v54, 16, 1
	v_add3_u32 v54, v54, v238, s1
	v_bfe_u32 v238, v55, 16, 1
	v_add3_u32 v55, v55, v238, s1
	v_bfe_u32 v238, v48, 16, 1
	v_add3_u32 v48, v48, v238, s1
	v_bfe_u32 v238, v49, 16, 1
	v_add3_u32 v49, v49, v238, s1
	v_bfe_u32 v238, v50, 16, 1
	v_add3_u32 v50, v50, v238, s1
	v_bfe_u32 v238, v51, 16, 1
	v_add3_u32 v51, v51, v238, s1
	v_cndmask_b32_e32 v220, v52, v53, vcc
	v_cndmask_b32_e32 v224, v53, v52, vcc
	v_cndmask_b32_e32 v221, v54, v55, vcc
	v_cndmask_b32_e32 v225, v55, v54, vcc
	v_cndmask_b32_e32 v222, v48, v49, vcc
	v_cndmask_b32_e32 v226, v49, v48, vcc
	v_cndmask_b32_e32 v223, v50, v51, vcc
	v_cndmask_b32_e32 v227, v51, v50, vcc
	v_lshl_add_u64 v[228:229], v[56:57], 0, v[232:233]
	v_mov_b32_dpp v224, v224 quad_perm:[1,0,3,2] row_mask:0xf bank_mask:0xf
	v_mov_b32_dpp v225, v225 quad_perm:[1,0,3,2] row_mask:0xf bank_mask:0xf
	v_mov_b32_dpp v226, v226 quad_perm:[1,0,3,2] row_mask:0xf bank_mask:0xf
	v_mov_b32_dpp v227, v227 quad_perm:[1,0,3,2] row_mask:0xf bank_mask:0xf
	s_nop 0
	v_perm_b32 v220, v224, v220, v236
	v_perm_b32 v221, v225, v221, v236
	v_perm_b32 v222, v226, v222, v236
	v_perm_b32 v223, v227, v223, v236
	v_cmp_ne_u32_e32 vcc, 0, v239
	s_nop 1
	v_cndmask_b32_e32 v224, v221, v220, vcc
	v_cndmask_b32_e32 v225, v223, v222, vcc
	s_nop 0
	v_mov_b32_dpp v224, v224 quad_perm:[2,3,0,1] row_mask:0xf bank_mask:0xf
	v_mov_b32_dpp v225, v225 quad_perm:[2,3,0,1] row_mask:0xf bank_mask:0xf
	s_nop 0
	v_cndmask_b32_e32 v220, v220, v224, vcc
	v_cndmask_b32_e32 v221, v224, v221, vcc
	v_cndmask_b32_e32 v222, v222, v225, vcc
	v_cndmask_b32_e32 v223, v225, v223, vcc
	global_store_dwordx2 v[228:229], v[220:221], off
	v_lshl_add_u64 v[228:229], v[228:229], 0, v[234:235]
	global_store_dwordx2 v[228:229], v[222:223], off

; __device__ __forceinline__ float rstd4(const float* pp, int row, float invn) { const f32x4 a = *(const f32x4*)(pp + (size_t)row * 4); return rsqrtf(((a.x + a.y) + (a.z + a.w)) * invn + 1e-6f); }
.LBB0_1137:
	v_or_b32_e32 v50, 16, v64
	v_readlane_b32 s44, v254, 12
	v_ashrrev_i32_e32 v51, 31, v50
	v_readlane_b32 s45, v254, 13
	s_mov_b32 s15, 0x800000
	s_nop 0
	v_lshl_add_u64 v[48:49], v[50:51], 4, s[44:45]
	s_mov_b64 s[44:45], -1
	v_mov_b32_e32 v52, v206
	v_mov_b32_e32 v53, v207
	v_mov_b32_e32 v54, v208
	v_mov_b32_e32 v55, v209
	v_mov_b32_e32 v48, v53
	v_mov_b32_e32 v49, v54
	v_mov_b32_e32 v53, v55
	v_pk_add_f32 v[48:49], v[48:49], v[52:53]
	s_nop 0
	v_add_f32_e32 v48, v48, v49
	v_fmamk_f32 v48, v48, 0x3c000000, v171
	v_cmp_gt_f32_e32 vcc, s15, v48
	v_mul_f32_e32 v49, 0x4b800000, v48
	s_movk_i32 s15, 0x7df
	v_cndmask_b32_e32 v48, v48, v49, vcc
	v_rsq_f32_e32 v48, v48
	s_nop 0
	v_mul_f32_e32 v49, 0x45800000, v48
	v_cndmask_b32_e32 v48, v48, v49, vcc
	v_bitop3_b32 v49, v64, s15, 16 bitop3:0xc8
	v_pk_mul_f32 v[46:47], v[46:47], v[48:49] op_sel_hi:[1,0]
	v_pk_mul_f32 v[44:45], v[44:45], v[48:49] op_sel_hi:[1,0]
	v_pk_mul_f32 v[42:43], v[42:43], v[48:49] op_sel_hi:[1,0]
	v_pk_mul_f32 v[40:41], v[40:41], v[48:49] op_sel_hi:[1,0]
	s_and_b64 vcc, exec, s[4:5]
	v_lshlrev_b32_e32 v52, 1, v49
	s_cbranch_vccnz .LBB0_1139
	s_add_i32 s44, s14, s50
	s_ashr_i32 s45, s44, 31
	s_lshl_b64 s[44:45], s[44:45], 18
	v_lshl_add_u64 v[54:55], v[138:139], 0, s[44:45]
	v_mov_b32_e32 v53, v145
	v_lshl_add_u64 v[54:55], v[54:55], 0, v[52:53]
	s_movk_i32 s15, 0x1000
	s_movk_i32 s15, 0x2000
	s_movk_i32 s15, 0x3000
	s_movk_i32 s15, 0x4000
	s_mov_b64 s[44:45], 0
	v_cmp_ne_u32_e32 vcc, 0, v237
	v_bfe_u32 v238, v44, 16, 1
	v_add3_u32 v44, v44, v238, s1
	v_bfe_u32 v238, v45, 16, 1
	v_add3_u32 v45, v45, v238, s1
	v_bfe_u32 v238, v46, 16, 1
	v_add3_u32 v46, v46, v238, s1
	v_bfe_u32 v238, v47, 16, 1
	v_add3_u32 v47, v47, v238, s1
	v_bfe_u32 v238, v40, 16, 1
	v_add3_u32 v40, v40, v238, s1
	v_bfe_u32 v238, v41, 16, 1
	v_add3_u32 v41, v41, v238, s1
	v_bfe_u32 v238, v42, 16, 1
	v_add3_u32 v42, v42, v238, s1
	v_bfe_u32 v238, v43, 16, 1
	v_add3_u32 v43, v43, v238, s1
	v_cndmask_b32_e32 v220, v44, v45, vcc
	v_cndmask_b32_e32 v224, v45, v44, vcc
	v_cndmask_b32_e32 v221, v46, v47, vcc
	v_cndmask_b32_e32 v225, v47, v46, vcc
	v_cndmask_b32_e32 v222, v40, v41, vcc
	v_cndmask_b32_e32 v226, v41, v40, vcc
	v_cndmask_b32_e32 v223, v42, v43, vcc
	v_cndmask_b32_e32 v227, v43, v42, vcc
	v_lshl_add_u64 v[228:229], v[54:55], 0, v[232:233]
	v_mov_b32_dpp v224, v224 quad_perm:[1,0,3,2] row_mask:0xf bank_mask:0xf
	v_mov_b32_dpp v225, v225 quad_perm:[1,0,3,2] row_mask:0xf bank_mask:0xf
	v_mov_b32_dpp v226, v226 quad_perm:[1,0,3,2] row_mask:0xf bank_mask:0xf
	v_mov_b32_dpp v227, v227 quad_perm:[1,0,3,2] row_mask:0xf bank_mask:0xf
	s_nop 0
	v_perm_b32 v220, v224, v220, v236
	v_perm_b32 v221, v225, v221, v236
	v_perm_b32 v222, v226, v222, v236
	v_perm_b32 v223, v227, v223, v236
	v_cmp_ne_u32_e32 vcc, 0, v239
	s_nop 1
	v_cndmask_b32_e32 v224, v221, v220, vcc
	v_cndmask_b32_e32 v225, v223, v222, vcc
	s_nop 0
	v_mov_b32_dpp v224, v224 quad_perm:[2,3,0,1] row_mask:0xf bank_mask:0xf
	v_mov_b32_dpp v225, v225 quad_perm:[2,3,0,1] row_mask:0xf bank_mask:0xf
	s_nop 0
	v_cndmask_b32_e32 v220, v220, v224, vcc
	v_cndmask_b32_e32 v221, v224, v221, vcc
	v_cndmask_b32_e32 v222, v222, v225, vcc
	v_cndmask_b32_e32 v223, v225, v223, vcc
	global_store_dwordx2 v[228:229], v[220:221], off
	v_lshl_add_u64 v[228:229], v[228:229], 0, v[234:235]
	global_store_dwordx2 v[228:229], v[222:223], off

.LBB0_1141:
	v_mov_b32_e32 v49, v48
	v_mov_b32_e32 v40, v48
	v_mov_b32_e32 v41, v48
	v_pk_mul_f32 v[38:39], v[38:39], v[40:41]
	v_pk_mul_f32 v[36:37], v[36:37], v[48:49]
	v_pk_mul_f32 v[34:35], v[34:35], v[40:41]
	v_pk_mul_f32 v[32:33], v[32:33], v[48:49]
	s_and_b64 vcc, exec, s[4:5]
	s_mov_b64 s[44:45], -1
	s_cbranch_vccnz .LBB0_1143
	s_add_i32 s44, s14, s51
	s_ashr_i32 s45, s44, 31
	s_lshl_b64 s[44:45], s[44:45], 18
	v_lshl_add_u64 v[40:41], v[138:139], 0, s[44:45]
	v_mov_b32_e32 v53, v145
	v_lshl_add_u64 v[40:41], v[40:41], 0, v[52:53]
	s_movk_i32 s15, 0x1000
	s_movk_i32 s15, 0x2000
	s_movk_i32 s15, 0x3000
	s_movk_i32 s15, 0x4000
	s_mov_b64 s[44:45], 0
	v_cmp_ne_u32_e32 vcc, 0, v237
	v_bfe_u32 v238, v36, 16, 1
	v_add3_u32 v36, v36, v238, s1
	v_bfe_u32 v238, v37, 16, 1
	v_add3_u32 v37, v37, v238, s1
	v_bfe_u32 v238, v38, 16, 1
	v_add3_u32 v38, v38, v238, s1
	v_bfe_u32 v238, v39, 16, 1
	v_add3_u32 v39, v39, v238, s1
	v_bfe_u32 v238, v32, 16, 1
	v_add3_u32 v32, v32, v238, s1
	v_bfe_u32 v238, v33, 16, 1
	v_add3_u32 v33, v33, v238, s1
	v_bfe_u32 v238, v34, 16, 1
	v_add3_u32 v34, v34, v238, s1
	v_bfe_u32 v238, v35, 16, 1
	v_add3_u32 v35, v35, v238, s1
	v_cndmask_b32_e32 v220, v36, v37, vcc
	v_cndmask_b32_e32 v224, v37, v36, vcc
	v_cndmask_b32_e32 v221, v38, v39, vcc
	v_cndmask_b32_e32 v225, v39, v38, vcc
	v_cndmask_b32_e32 v222, v32, v33, vcc
	v_cndmask_b32_e32 v226, v33, v32, vcc
	v_cndmask_b32_e32 v223, v34, v35, vcc
	v_cndmask_b32_e32 v227, v35, v34, vcc
	v_lshl_add_u64 v[228:229], v[40:41], 0, v[232:233]
	v_mov_b32_dpp v224, v224 quad_perm:[1,0,3,2] row_mask:0xf bank_mask:0xf
	v_mov_b32_dpp v225, v225 quad_perm:[1,0,3,2] row_mask:0xf bank_mask:0xf
	v_mov_b32_dpp v226, v226 quad_perm:[1,0,3,2] row_mask:0xf bank_mask:0xf
	v_mov_b32_dpp v227, v227 quad_perm:[1,0,3,2] row_mask:0xf bank_mask:0xf
	s_nop 0
	v_perm_b32 v220, v224, v220, v236
	v_perm_b32 v221, v225, v221, v236
	v_perm_b32 v222, v226, v222, v236
	v_perm_b32 v223, v227, v223, v236
	v_cmp_ne_u32_e32 vcc, 0, v239
	s_nop 1
	v_cndmask_b32_e32 v224, v221, v220, vcc
	v_cndmask_b32_e32 v225, v223, v222, vcc
	s_nop 0
	v_mov_b32_dpp v224, v224 quad_perm:[2,3,0,1] row_mask:0xf bank_mask:0xf
	v_mov_b32_dpp v225, v225 quad_perm:[2,3,0,1] row_mask:0xf bank_mask:0xf
	s_nop 0
	v_cndmask_b32_e32 v220, v220, v224, vcc
	v_cndmask_b32_e32 v221, v224, v221, vcc
	v_cndmask_b32_e32 v222, v222, v225, vcc
	v_cndmask_b32_e32 v223, v225, v223, vcc
	global_store_dwordx2 v[228:229], v[220:221], off
	v_lshl_add_u64 v[228:229], v[228:229], 0, v[234:235]
	global_store_dwordx2 v[228:229], v[222:223], off

; __device__ __forceinline__ float rstd4(const float* pp, int row, float invn) { const f32x4 a = *(const f32x4*)(pp + (size_t)row * 4); return rsqrtf(((a.x + a.y) + (a.z + a.w)) * invn + 1e-6f); }
.LBB0_1145:
	v_or_b32_e32 v34, 32, v64
	v_readlane_b32 s44, v254, 12
	v_ashrrev_i32_e32 v35, 31, v34
	v_readlane_b32 s45, v254, 13
	s_mov_b32 s15, 0x800000
	s_nop 0
	v_lshl_add_u64 v[32:33], v[34:35], 4, s[44:45]
	s_mov_b64 s[44:45], -1
	v_mov_b32_e32 v36, v210
	v_mov_b32_e32 v37, v211
	v_mov_b32_e32 v38, v212
	v_mov_b32_e32 v39, v213
	v_mov_b32_e32 v32, v37
	v_mov_b32_e32 v33, v38
	v_mov_b32_e32 v37, v39
	v_pk_add_f32 v[32:33], v[32:33], v[36:37]
	s_nop 0
	v_add_f32_e32 v32, v32, v33
	v_fmamk_f32 v32, v32, 0x3c000000, v171
	v_cmp_gt_f32_e32 vcc, s15, v32
	v_mul_f32_e32 v33, 0x4b800000, v32
	s_movk_i32 s15, 0x7ef
	v_cndmask_b32_e32 v32, v32, v33, vcc
	v_rsq_f32_e32 v32, v32
	s_nop 0
	v_mul_f32_e32 v33, 0x45800000, v32
	v_cndmask_b32_e32 v32, v32, v33, vcc
	v_bitop3_b32 v33, v64, s15, 32 bitop3:0xc8
	v_pk_mul_f32 v[30:31], v[30:31], v[32:33] op_sel_hi:[1,0]
	v_pk_mul_f32 v[28:29], v[28:29], v[32:33] op_sel_hi:[1,0]
	v_pk_mul_f32 v[26:27], v[26:27], v[32:33] op_sel_hi:[1,0]
	v_pk_mul_f32 v[24:25], v[24:25], v[32:33] op_sel_hi:[1,0]
	s_and_b64 vcc, exec, s[4:5]
	v_lshlrev_b32_e32 v36, 1, v33
	s_cbranch_vccnz .LBB0_1147
	s_add_i32 s44, s14, s50
	s_ashr_i32 s45, s44, 31
	s_lshl_b64 s[44:45], s[44:45], 18
	v_lshl_add_u64 v[38:39], v[138:139], 0, s[44:45]
	v_mov_b32_e32 v37, v145
	v_lshl_add_u64 v[38:39], v[38:39], 0, v[36:37]
	s_movk_i32 s15, 0x1000
	s_movk_i32 s15, 0x2000
	s_movk_i32 s15, 0x3000
	s_movk_i32 s15, 0x4000
	s_mov_b64 s[44:45], 0
	v_cmp_ne_u32_e32 vcc, 0, v237
	v_bfe_u32 v238, v28, 16, 1
	v_add3_u32 v28, v28, v238, s1
	v_bfe_u32 v238, v29, 16, 1
	v_add3_u32 v29, v29, v238, s1
	v_bfe_u32 v238, v30, 16, 1
	v_add3_u32 v30, v30, v238, s1
	v_bfe_u32 v238, v31, 16, 1
	v_add3_u32 v31, v31, v238, s1
	v_bfe_u32 v238, v24, 16, 1
	v_add3_u32 v24, v24, v238, s1
	v_bfe_u32 v238, v25, 16, 1
	v_add3_u32 v25, v25, v238, s1
	v_bfe_u32 v238, v26, 16, 1
	v_add3_u32 v26, v26, v238, s1
	v_bfe_u32 v238, v27, 16, 1
	v_add3_u32 v27, v27, v238, s1
	v_cndmask_b32_e32 v220, v28, v29, vcc
	v_cndmask_b32_e32 v224, v29, v28, vcc
	v_cndmask_b32_e32 v221, v30, v31, vcc
	v_cndmask_b32_e32 v225, v31, v30, vcc
	v_cndmask_b32_e32 v222, v24, v25, vcc
	v_cndmask_b32_e32 v226, v25, v24, vcc
	v_cndmask_b32_e32 v223, v26, v27, vcc
	v_cndmask_b32_e32 v227, v27, v26, vcc
	v_lshl_add_u64 v[228:229], v[38:39], 0, v[232:233]
	v_mov_b32_dpp v224, v224 quad_perm:[1,0,3,2] row_mask:0xf bank_mask:0xf
	v_mov_b32_dpp v225, v225 quad_perm:[1,0,3,2] row_mask:0xf bank_mask:0xf
	v_mov_b32_dpp v226, v226 quad_perm:[1,0,3,2] row_mask:0xf bank_mask:0xf
	v_mov_b32_dpp v227, v227 quad_perm:[1,0,3,2] row_mask:0xf bank_mask:0xf
	s_nop 0
	v_perm_b32 v220, v224, v220, v236
	v_perm_b32 v221, v225, v221, v236
	v_perm_b32 v222, v226, v222, v236
	v_perm_b32 v223, v227, v223, v236
	v_cmp_ne_u32_e32 vcc, 0, v239
	s_nop 1
	v_cndmask_b32_e32 v224, v221, v220, vcc
	v_cndmask_b32_e32 v225, v223, v222, vcc
	s_nop 0
	v_mov_b32_dpp v224, v224 quad_perm:[2,3,0,1] row_mask:0xf bank_mask:0xf
	v_mov_b32_dpp v225, v225 quad_perm:[2,3,0,1] row_mask:0xf bank_mask:0xf
	s_nop 0
	v_cndmask_b32_e32 v220, v220, v224, vcc
	v_cndmask_b32_e32 v221, v224, v221, vcc
	v_cndmask_b32_e32 v222, v222, v225, vcc
	v_cndmask_b32_e32 v223, v225, v223, vcc
	global_store_dwordx2 v[228:229], v[220:221], off
	v_lshl_add_u64 v[228:229], v[228:229], 0, v[234:235]
	global_store_dwordx2 v[228:229], v[222:223], off

.LBB0_1149:
	v_mov_b32_e32 v33, v32
	v_mov_b32_e32 v24, v32
	v_mov_b32_e32 v25, v32
	v_pk_mul_f32 v[22:23], v[22:23], v[24:25]
	v_pk_mul_f32 v[20:21], v[20:21], v[32:33]
	v_pk_mul_f32 v[18:19], v[18:19], v[24:25]
	v_pk_mul_f32 v[16:17], v[16:17], v[32:33]
	s_and_b64 vcc, exec, s[4:5]
	s_mov_b64 s[44:45], -1
	s_cbranch_vccnz .LBB0_1151
	s_add_i32 s44, s14, s51
	s_ashr_i32 s45, s44, 31
	s_lshl_b64 s[44:45], s[44:45], 18
	v_lshl_add_u64 v[24:25], v[138:139], 0, s[44:45]
	v_mov_b32_e32 v37, v145
	v_lshl_add_u64 v[24:25], v[24:25], 0, v[36:37]
	s_movk_i32 s15, 0x1000
	s_movk_i32 s15, 0x2000
	s_movk_i32 s15, 0x3000
	s_movk_i32 s15, 0x4000
	s_mov_b64 s[44:45], 0
	v_cmp_ne_u32_e32 vcc, 0, v237
	v_bfe_u32 v238, v20, 16, 1
	v_add3_u32 v20, v20, v238, s1
	v_bfe_u32 v238, v21, 16, 1
	v_add3_u32 v21, v21, v238, s1
	v_bfe_u32 v238, v22, 16, 1
	v_add3_u32 v22, v22, v238, s1
	v_bfe_u32 v238, v23, 16, 1
	v_add3_u32 v23, v23, v238, s1
	v_bfe_u32 v238, v16, 16, 1
	v_add3_u32 v16, v16, v238, s1
	v_bfe_u32 v238, v17, 16, 1
	v_add3_u32 v17, v17, v238, s1
	v_bfe_u32 v238, v18, 16, 1
	v_add3_u32 v18, v18, v238, s1
	v_bfe_u32 v238, v19, 16, 1
	v_add3_u32 v19, v19, v238, s1
	v_cndmask_b32_e32 v220, v20, v21, vcc
	v_cndmask_b32_e32 v224, v21, v20, vcc
	v_cndmask_b32_e32 v221, v22, v23, vcc
	v_cndmask_b32_e32 v225, v23, v22, vcc
	v_cndmask_b32_e32 v222, v16, v17, vcc
	v_cndmask_b32_e32 v226, v17, v16, vcc
	v_cndmask_b32_e32 v223, v18, v19, vcc
	v_cndmask_b32_e32 v227, v19, v18, vcc
	v_lshl_add_u64 v[228:229], v[24:25], 0, v[232:233]
	v_mov_b32_dpp v224, v224 quad_perm:[1,0,3,2] row_mask:0xf bank_mask:0xf
	v_mov_b32_dpp v225, v225 quad_perm:[1,0,3,2] row_mask:0xf bank_mask:0xf
	v_mov_b32_dpp v226, v226 quad_perm:[1,0,3,2] row_mask:0xf bank_mask:0xf
	v_mov_b32_dpp v227, v227 quad_perm:[1,0,3,2] row_mask:0xf bank_mask:0xf
	s_nop 0
	v_perm_b32 v220, v224, v220, v236
	v_perm_b32 v221, v225, v221, v236
	v_perm_b32 v222, v226, v222, v236
	v_perm_b32 v223, v227, v223, v236
	v_cmp_ne_u32_e32 vcc, 0, v239
	s_nop 1
	v_cndmask_b32_e32 v224, v221, v220, vcc
	v_cndmask_b32_e32 v225, v223, v222, vcc
	s_nop 0
	v_mov_b32_dpp v224, v224 quad_perm:[2,3,0,1] row_mask:0xf bank_mask:0xf
	v_mov_b32_dpp v225, v225 quad_perm:[2,3,0,1] row_mask:0xf bank_mask:0xf
	s_nop 0
	v_cndmask_b32_e32 v220, v220, v224, vcc
	v_cndmask_b32_e32 v221, v224, v221, vcc
	v_cndmask_b32_e32 v222, v222, v225, vcc
	v_cndmask_b32_e32 v223, v225, v223, vcc
	global_store_dwordx2 v[228:229], v[220:221], off
	v_lshl_add_u64 v[228:229], v[228:229], 0, v[234:235]
	global_store_dwordx2 v[228:229], v[222:223], off

; __device__ __forceinline__ float rstd4(const float* pp, int row, float invn) { const f32x4 a = *(const f32x4*)(pp + (size_t)row * 4); return rsqrtf(((a.x + a.y) + (a.z + a.w)) * invn + 1e-6f); }
.LBB0_1153:
	v_or_b32_e32 v18, 48, v64
	v_readlane_b32 s44, v254, 12
	v_ashrrev_i32_e32 v19, 31, v18
	v_readlane_b32 s45, v254, 13
	s_mov_b32 s15, 0x800000
	s_nop 0
	v_lshl_add_u64 v[16:17], v[18:19], 4, s[44:45]
	s_mov_b64 s[44:45], -1
	v_mov_b32_e32 v20, v214
	v_mov_b32_e32 v21, v215
	v_mov_b32_e32 v22, v216
	v_mov_b32_e32 v23, v217
	v_mov_b32_e32 v16, v21
	v_mov_b32_e32 v17, v22
	v_mov_b32_e32 v21, v23
	v_pk_add_f32 v[16:17], v[16:17], v[20:21]
	s_nop 0
	v_add_f32_e32 v16, v16, v17
	v_fmamk_f32 v16, v16, 0x3c000000, v171
	v_cmp_gt_f32_e32 vcc, s15, v16
	v_mul_f32_e32 v17, 0x4b800000, v16
	s_movk_i32 s15, 0x7ff
	v_cndmask_b32_e32 v16, v16, v17, vcc
	v_rsq_f32_e32 v16, v16
	s_nop 0
	v_mul_f32_e32 v17, 0x45800000, v16
	v_cndmask_b32_e32 v16, v16, v17, vcc
	v_bitop3_b32 v17, v64, s15, 48 bitop3:0xc8
	v_pk_mul_f32 v[14:15], v[14:15], v[16:17] op_sel_hi:[1,0]
	v_pk_mul_f32 v[12:13], v[12:13], v[16:17] op_sel_hi:[1,0]
	v_pk_mul_f32 v[10:11], v[10:11], v[16:17] op_sel_hi:[1,0]
	v_pk_mul_f32 v[8:9], v[8:9], v[16:17] op_sel_hi:[1,0]
	s_and_b64 vcc, exec, s[4:5]
	v_lshlrev_b32_e32 v20, 1, v17
	s_cbranch_vccnz .LBB0_1155
	s_add_i32 s44, s14, s50
	s_ashr_i32 s45, s44, 31
	s_lshl_b64 s[44:45], s[44:45], 18
	v_lshl_add_u64 v[22:23], v[138:139], 0, s[44:45]
	v_mov_b32_e32 v21, v145
	v_lshl_add_u64 v[22:23], v[22:23], 0, v[20:21]
	s_movk_i32 s15, 0x1000
	s_movk_i32 s15, 0x2000
	s_movk_i32 s15, 0x3000
	s_movk_i32 s15, 0x4000
	s_mov_b64 s[44:45], 0
	v_cmp_ne_u32_e32 vcc, 0, v237
	v_bfe_u32 v238, v12, 16, 1
	v_add3_u32 v12, v12, v238, s1
	v_bfe_u32 v238, v13, 16, 1
	v_add3_u32 v13, v13, v238, s1
	v_bfe_u32 v238, v14, 16, 1
	v_add3_u32 v14, v14, v238, s1
	v_bfe_u32 v238, v15, 16, 1
	v_add3_u32 v15, v15, v238, s1
	v_bfe_u32 v238, v8, 16, 1
	v_add3_u32 v8, v8, v238, s1
	v_bfe_u32 v238, v9, 16, 1
	v_add3_u32 v9, v9, v238, s1
	v_bfe_u32 v238, v10, 16, 1
	v_add3_u32 v10, v10, v238, s1
	v_bfe_u32 v238, v11, 16, 1
	v_add3_u32 v11, v11, v238, s1
	v_cndmask_b32_e32 v220, v12, v13, vcc
	v_cndmask_b32_e32 v224, v13, v12, vcc
	v_cndmask_b32_e32 v221, v14, v15, vcc
	v_cndmask_b32_e32 v225, v15, v14, vcc
	v_cndmask_b32_e32 v222, v8, v9, vcc
	v_cndmask_b32_e32 v226, v9, v8, vcc
	v_cndmask_b32_e32 v223, v10, v11, vcc
	v_cndmask_b32_e32 v227, v11, v10, vcc
	v_lshl_add_u64 v[228:229], v[22:23], 0, v[232:233]
	v_mov_b32_dpp v224, v224 quad_perm:[1,0,3,2] row_mask:0xf bank_mask:0xf
	v_mov_b32_dpp v225, v225 quad_perm:[1,0,3,2] row_mask:0xf bank_mask:0xf
	v_mov_b32_dpp v226, v226 quad_perm:[1,0,3,2] row_mask:0xf bank_mask:0xf
	v_mov_b32_dpp v227, v227 quad_perm:[1,0,3,2] row_mask:0xf bank_mask:0xf
	s_nop 0
	v_perm_b32 v220, v224, v220, v236
	v_perm_b32 v221, v225, v221, v236
	v_perm_b32 v222, v226, v222, v236
	v_perm_b32 v223, v227, v223, v236
	v_cmp_ne_u32_e32 vcc, 0, v239
	s_nop 1
	v_cndmask_b32_e32 v224, v221, v220, vcc
	v_cndmask_b32_e32 v225, v223, v222, vcc
	s_nop 0
	v_mov_b32_dpp v224, v224 quad_perm:[2,3,0,1] row_mask:0xf bank_mask:0xf
	v_mov_b32_dpp v225, v225 quad_perm:[2,3,0,1] row_mask:0xf bank_mask:0xf
	s_nop 0
	v_cndmask_b32_e32 v220, v220, v224, vcc
	v_cndmask_b32_e32 v221, v224, v221, vcc
	v_cndmask_b32_e32 v222, v222, v225, vcc
	v_cndmask_b32_e32 v223, v225, v223, vcc
	global_store_dwordx2 v[228:229], v[220:221], off
	v_lshl_add_u64 v[228:229], v[228:229], 0, v[234:235]
	global_store_dwordx2 v[228:229], v[222:223], off

.LBB0_1160:
	s_add_i32 s4, s14, s51
	s_ashr_i32 s5, s4, 31
	s_lshl_b64 s[4:5], s[4:5], 18
	v_lshl_add_u64 v[8:9], v[138:139], 0, s[4:5]
	v_mov_b32_e32 v21, v145
	v_lshl_add_u64 v[8:9], v[8:9], 0, v[20:21]
	s_movk_i32 s4, 0x1000
	s_movk_i32 s4, 0x2000
	s_movk_i32 s4, 0x3000
	s_movk_i32 s4, 0x4000
	v_cmp_ne_u32_e32 vcc, 0, v237
	v_bfe_u32 v238, v4, 16, 1
	v_add3_u32 v4, v4, v238, s1
	v_bfe_u32 v238, v5, 16, 1
	v_add3_u32 v5, v5, v238, s1
	v_bfe_u32 v238, v6, 16, 1
	v_add3_u32 v6, v6, v238, s1
	v_bfe_u32 v238, v7, 16, 1
	v_add3_u32 v7, v7, v238, s1
	v_bfe_u32 v238, v0, 16, 1
	v_add3_u32 v0, v0, v238, s1
	v_bfe_u32 v238, v1, 16, 1
	v_add3_u32 v1, v1, v238, s1
	v_bfe_u32 v238, v2, 16, 1
	v_add3_u32 v2, v2, v238, s1
	v_bfe_u32 v238, v3, 16, 1
	v_add3_u32 v3, v3, v238, s1
	v_cndmask_b32_e32 v220, v4, v5, vcc
	v_cndmask_b32_e32 v224, v5, v4, vcc
	v_cndmask_b32_e32 v221, v6, v7, vcc
	v_cndmask_b32_e32 v225, v7, v6, vcc
	v_cndmask_b32_e32 v222, v0, v1, vcc
	v_cndmask_b32_e32 v226, v1, v0, vcc
	v_cndmask_b32_e32 v223, v2, v3, vcc
	v_cndmask_b32_e32 v227, v3, v2, vcc
	v_lshl_add_u64 v[228:229], v[8:9], 0, v[232:233]
	v_mov_b32_dpp v224, v224 quad_perm:[1,0,3,2] row_mask:0xf bank_mask:0xf
	v_mov_b32_dpp v225, v225 quad_perm:[1,0,3,2] row_mask:0xf bank_mask:0xf
	v_mov_b32_dpp v226, v226 quad_perm:[1,0,3,2] row_mask:0xf bank_mask:0xf
	v_mov_b32_dpp v227, v227 quad_perm:[1,0,3,2] row_mask:0xf bank_mask:0xf
	s_nop 0
	v_perm_b32 v220, v224, v220, v236
	v_perm_b32 v221, v225, v221, v236
	v_perm_b32 v222, v226, v222, v236
	v_perm_b32 v223, v227, v223, v236
	v_cmp_ne_u32_e32 vcc, 0, v239
	s_nop 1
	v_cndmask_b32_e32 v224, v221, v220, vcc
	v_cndmask_b32_e32 v225, v223, v222, vcc
	s_nop 0
	v_mov_b32_dpp v224, v224 quad_perm:[2,3,0,1] row_mask:0xf bank_mask:0xf
	v_mov_b32_dpp v225, v225 quad_perm:[2,3,0,1] row_mask:0xf bank_mask:0xf
	s_nop 0
	v_cndmask_b32_e32 v220, v220, v224, vcc
	v_cndmask_b32_e32 v221, v224, v221, vcc
	v_cndmask_b32_e32 v222, v222, v225, vcc
	v_cndmask_b32_e32 v223, v225, v223, vcc
	global_store_dwordx2 v[228:229], v[220:221], off
	v_lshl_add_u64 v[228:229], v[228:229], 0, v[234:235]
	global_store_dwordx2 v[228:229], v[222:223], off
	s_cbranch_execnz .LBB0_1159

.LBB0_1851:
	v_mbcnt_lo_u32_b32 v237, -1, 0
	v_mbcnt_hi_u32_b32 v237, -1, v237
	v_bfe_u32 v239, v237, 1, 1
	v_and_b32_e32 v238, 3, v237
	v_mul_u32_u24_e32 v232, 0x1fe, v238
	v_and_b32_e32 v237, 1, v237
	v_mov_b32_e32 v233, 0
	v_mov_b32_e32 v236, 0x7060302
	v_mov_b32_e32 v238, 0x3020706
	v_cmp_ne_u32_e32 vcc, 0, v237
	s_nop 1
	v_cndmask_b32_e32 v236, v236, v238, vcc
	s_lshl_b32 s28, s53, 8
	s_add_i32 s28, s28, s46
	s_ashr_i32 s29, s28, 6
	s_and_b32 s29, s29, -4
	s_add_i32 s56, s29, s51
	s_lshl_b32 s26, s51, 7
	s_ashr_i32 s57, s56, 31
	s_ashr_i32 s27, s26, 31
	v_or_b32_e32 v156, s28, v142
	s_lshl_b64 s[56:57], s[56:57], 16
	v_ashrrev_i32_e32 v157, 31, v156
	v_cvt_pk_bf16_f32 v124, v124, v125
	v_cvt_pk_bf16_f32 v125, v126, v127
	v_cvt_pk_bf16_f32 v126, v120, v121
	v_lshlrev_b64 v[120:121], 10, v[156:157]
	v_lshl_add_u64 v[120:121], s[14:15], 0, v[120:121]
	s_lshl_b64 s[26:27], s[26:27], 1
	v_lshl_add_u64 v[120:121], v[120:121], 0, s[26:27]
	v_cvt_pk_bf16_f32 v127, v122, v123
	v_lshl_add_u64 v[120:121], v[120:121], 0, v[144:145]
	v_bitop3_b32 v122, s28, v184, v142 bitop3:0xc8
	flat_store_dwordx4 v[120:121], v[124:127]
	v_lshl_add_u64 v[120:121], v[136:137], 0, s[56:57]
	v_lshlrev_b32_e32 v122, 1, v122
	v_mov_b32_e32 v123, v145
	v_lshl_add_u64 v[122:123], v[120:121], 0, v[122:123]
	v_cmp_ne_u32_e32 vcc, 0, v237
	v_bfe_u32 v238, v104, 16, 1
	v_add3_u32 v104, v104, v238, s1
	v_bfe_u32 v238, v105, 16, 1
	v_add3_u32 v105, v105, v238, s1
	v_bfe_u32 v238, v106, 16, 1
	v_add3_u32 v106, v106, v238, s1
	v_bfe_u32 v238, v107, 16, 1
	v_add3_u32 v107, v107, v238, s1
	v_bfe_u32 v238, v116, 16, 1
	v_add3_u32 v116, v116, v238, s1
	v_bfe_u32 v238, v117, 16, 1
	v_add3_u32 v117, v117, v238, s1
	v_bfe_u32 v238, v118, 16, 1
	v_add3_u32 v118, v118, v238, s1
	v_bfe_u32 v238, v119, 16, 1
	v_add3_u32 v119, v119, v238, s1
	v_cndmask_b32_e32 v220, v104, v105, vcc
	v_cndmask_b32_e32 v224, v105, v104, vcc
	v_cndmask_b32_e32 v221, v106, v107, vcc
	v_cndmask_b32_e32 v225, v107, v106, vcc
	v_cndmask_b32_e32 v222, v116, v117, vcc
	v_cndmask_b32_e32 v226, v117, v116, vcc
	v_cndmask_b32_e32 v223, v118, v119, vcc
	v_cndmask_b32_e32 v227, v119, v118, vcc
	v_lshl_add_u64 v[228:229], v[122:123], 0, v[232:233]
	v_mov_b32_dpp v224, v224 quad_perm:[1,0,3,2] row_mask:0xf bank_mask:0xf
	v_mov_b32_dpp v225, v225 quad_perm:[1,0,3,2] row_mask:0xf bank_mask:0xf
	v_mov_b32_dpp v226, v226 quad_perm:[1,0,3,2] row_mask:0xf bank_mask:0xf
	v_mov_b32_dpp v227, v227 quad_perm:[1,0,3,2] row_mask:0xf bank_mask:0xf
	s_nop 0
	v_perm_b32 v220, v224, v220, v236
	v_perm_b32 v221, v225, v221, v236
	v_perm_b32 v222, v226, v222, v236
	v_perm_b32 v223, v227, v223, v236
	v_cmp_ne_u32_e32 vcc, 0, v239
	s_nop 1
	v_cndmask_b32_e32 v224, v221, v220, vcc
	v_cndmask_b32_e32 v225, v223, v222, vcc
	s_nop 0
	v_mov_b32_dpp v224, v224 quad_perm:[2,3,0,1] row_mask:0xf bank_mask:0xf
	v_mov_b32_dpp v225, v225 quad_perm:[2,3,0,1] row_mask:0xf bank_mask:0xf
	s_nop 0
	v_cndmask_b32_e32 v220, v220, v224, vcc
	v_cndmask_b32_e32 v221, v224, v221, vcc
	v_cndmask_b32_e32 v222, v222, v225, vcc
	v_cndmask_b32_e32 v223, v225, v223, vcc
	global_store_dwordx2 v[228:229], v[220:221], off
	global_store_dwordx2 v[228:229], v[222:223], off offset:2048
	v_or_b32_e32 v116, 16, v156
	v_ashrrev_i32_e32 v117, 31, v116
	v_cvt_pk_bf16_f32 v106, v108, v109
	v_lshlrev_b64 v[108:109], 10, v[116:117]
	v_lshl_add_u64 v[108:109], s[14:15], 0, v[108:109]
	v_lshl_add_u64 v[108:109], v[108:109], 0, s[26:27]
	v_cvt_pk_bf16_f32 v104, v112, v113
	v_cvt_pk_bf16_f32 v105, v114, v115
	v_cvt_pk_bf16_f32 v107, v110, v111
	v_lshl_add_u64 v[108:109], v[108:109], 0, v[144:145]
	s_movk_i32 s56, 0xdf
	flat_store_dwordx4 v[108:109], v[104:107]
	s_nop 1
	v_bitop3_b32 v104, v156, s56, 16 bitop3:0xc8
	v_lshlrev_b32_e32 v104, 1, v104
	v_mov_b32_e32 v105, v145
	v_lshl_add_u64 v[104:105], v[120:121], 0, v[104:105]
	v_cmp_ne_u32_e32 vcc, 0, v237
	v_bfe_u32 v238, v100, 16, 1
	v_add3_u32 v100, v100, v238, s1
	v_bfe_u32 v238, v101, 16, 1
	v_add3_u32 v101, v101, v238, s1
	v_bfe_u32 v238, v102, 16, 1
	v_add3_u32 v102, v102, v238, s1
	v_bfe_u32 v238, v103, 16, 1
	v_add3_u32 v103, v103, v238, s1
	v_bfe_u32 v238, v96, 16, 1
	v_add3_u32 v96, v96, v238, s1
	v_bfe_u32 v238, v97, 16, 1
	v_add3_u32 v97, v97, v238, s1
	v_bfe_u32 v238, v98, 16, 1
	v_add3_u32 v98, v98, v238, s1
	v_bfe_u32 v238, v99, 16, 1
	v_add3_u32 v99, v99, v238, s1
	v_cndmask_b32_e32 v220, v100, v101, vcc
	v_cndmask_b32_e32 v224, v101, v100, vcc
	v_cndmask_b32_e32 v221, v102, v103, vcc
	v_cndmask_b32_e32 v225, v103, v102, vcc
	v_cndmask_b32_e32 v222, v96, v97, vcc
	v_cndmask_b32_e32 v226, v97, v96, vcc
	v_cndmask_b32_e32 v223, v98, v99, vcc
	v_cndmask_b32_e32 v227, v99, v98, vcc
	v_lshl_add_u64 v[228:229], v[104:105], 0, v[232:233]
	v_mov_b32_dpp v224, v224 quad_perm:[1,0,3,2] row_mask:0xf bank_mask:0xf
	v_mov_b32_dpp v225, v225 quad_perm:[1,0,3,2] row_mask:0xf bank_mask:0xf
	v_mov_b32_dpp v226, v226 quad_perm:[1,0,3,2] row_mask:0xf bank_mask:0xf
	v_mov_b32_dpp v227, v227 quad_perm:[1,0,3,2] row_mask:0xf bank_mask:0xf
	s_nop 0
	v_perm_b32 v220, v224, v220, v236
	v_perm_b32 v221, v225, v221, v236
	v_perm_b32 v222, v226, v222, v236
	v_perm_b32 v223, v227, v223, v236
	v_cmp_ne_u32_e32 vcc, 0, v239
	s_nop 1
	v_cndmask_b32_e32 v224, v221, v220, vcc
	v_cndmask_b32_e32 v225, v223, v222, vcc
	s_nop 0
	v_mov_b32_dpp v224, v224 quad_perm:[2,3,0,1] row_mask:0xf bank_mask:0xf
	v_mov_b32_dpp v225, v225 quad_perm:[2,3,0,1] row_mask:0xf bank_mask:0xf
	s_nop 0
	v_cndmask_b32_e32 v220, v220, v224, vcc
	v_cndmask_b32_e32 v221, v224, v221, vcc
	v_cndmask_b32_e32 v222, v222, v225, vcc
	v_cndmask_b32_e32 v223, v225, v223, vcc
	global_store_dwordx2 v[228:229], v[220:221], off
	global_store_dwordx2 v[228:229], v[222:223], off offset:2048
	v_or_b32_e32 v96, 32, v156
	v_ashrrev_i32_e32 v97, 31, v96
	v_cvt_pk_bf16_f32 v92, v92, v93
	v_cvt_pk_bf16_f32 v93, v94, v95
	v_cvt_pk_bf16_f32 v94, v88, v89
	v_lshlrev_b64 v[88:89], 10, v[96:97]
	v_lshl_add_u64 v[88:89], s[14:15], 0, v[88:89]
	v_lshl_add_u64 v[88:89], v[88:89], 0, s[26:27]
	v_cvt_pk_bf16_f32 v95, v90, v91
	v_lshl_add_u64 v[88:89], v[88:89], 0, v[144:145]
	s_movk_i32 s57, 0xef
	flat_store_dwordx4 v[88:89], v[92:95]
	v_bitop3_b32 v88, v156, s57, 32 bitop3:0xc8
	v_lshlrev_b32_e32 v88, 1, v88
	v_mov_b32_e32 v89, v145
	v_lshl_add_u64 v[88:89], v[120:121], 0, v[88:89]
	v_cmp_ne_u32_e32 vcc, 0, v237
	v_bfe_u32 v238, v84, 16, 1
	v_add3_u32 v84, v84, v238, s1
	v_bfe_u32 v238, v85, 16, 1
	v_add3_u32 v85, v85, v238, s1
	v_bfe_u32 v238, v86, 16, 1
	v_add3_u32 v86, v86, v238, s1
	v_bfe_u32 v238, v87, 16, 1
	v_add3_u32 v87, v87, v238, s1
	v_bfe_u32 v238, v80, 16, 1
	v_add3_u32 v80, v80, v238, s1
	v_bfe_u32 v238, v81, 16, 1
	v_add3_u32 v81, v81, v238, s1
	v_bfe_u32 v238, v82, 16, 1
	v_add3_u32 v82, v82, v238, s1
	v_bfe_u32 v238, v83, 16, 1
	v_add3_u32 v83, v83, v238, s1
	v_cndmask_b32_e32 v220, v84, v85, vcc
	v_cndmask_b32_e32 v224, v85, v84, vcc
	v_cndmask_b32_e32 v221, v86, v87, vcc
	v_cndmask_b32_e32 v225, v87, v86, vcc
	v_cndmask_b32_e32 v222, v80, v81, vcc
	v_cndmask_b32_e32 v226, v81, v80, vcc
	v_cndmask_b32_e32 v223, v82, v83, vcc
	v_cndmask_b32_e32 v227, v83, v82, vcc
	v_lshl_add_u64 v[228:229], v[88:89], 0, v[232:233]
	v_mov_b32_dpp v224, v224 quad_perm:[1,0,3,2] row_mask:0xf bank_mask:0xf
	v_mov_b32_dpp v225, v225 quad_perm:[1,0,3,2] row_mask:0xf bank_mask:0xf
	v_mov_b32_dpp v226, v226 quad_perm:[1,0,3,2] row_mask:0xf bank_mask:0xf
	v_mov_b32_dpp v227, v227 quad_perm:[1,0,3,2] row_mask:0xf bank_mask:0xf
	s_nop 0
	v_perm_b32 v220, v224, v220, v236
	v_perm_b32 v221, v225, v221, v236
	v_perm_b32 v222, v226, v222, v236
	v_perm_b32 v223, v227, v223, v236
	v_cmp_ne_u32_e32 vcc, 0, v239
	s_nop 1
	v_cndmask_b32_e32 v224, v221, v220, vcc
	v_cndmask_b32_e32 v225, v223, v222, vcc
	s_nop 0
	v_mov_b32_dpp v224, v224 quad_perm:[2,3,0,1] row_mask:0xf bank_mask:0xf
	v_mov_b32_dpp v225, v225 quad_perm:[2,3,0,1] row_mask:0xf bank_mask:0xf
	s_nop 0
	v_cndmask_b32_e32 v220, v220, v224, vcc
	v_cndmask_b32_e32 v221, v224, v221, vcc
	v_cndmask_b32_e32 v222, v222, v225, vcc
	v_cndmask_b32_e32 v223, v225, v223, vcc
	global_store_dwordx2 v[228:229], v[220:221], off
	global_store_dwordx2 v[228:229], v[222:223], off offset:2048
	v_or_b32_e32 v80, 48, v156
	v_ashrrev_i32_e32 v81, 31, v80
	v_cvt_pk_bf16_f32 v76, v76, v77
	v_cvt_pk_bf16_f32 v77, v78, v79
	v_cvt_pk_bf16_f32 v78, v72, v73
	v_lshlrev_b64 v[72:73], 10, v[80:81]
	v_lshl_add_u64 v[72:73], s[14:15], 0, v[72:73]
	v_lshl_add_u64 v[72:73], v[72:73], 0, s[26:27]
	v_cvt_pk_bf16_f32 v79, v74, v75
	v_lshl_add_u64 v[72:73], v[72:73], 0, v[144:145]
	s_movk_i32 s53, 0xff
	flat_store_dwordx4 v[72:73], v[76:79]
	v_bitop3_b32 v72, v156, s53, 48 bitop3:0xc8
	v_lshlrev_b32_e32 v72, 1, v72
	v_mov_b32_e32 v73, v145
	v_lshl_add_u64 v[72:73], v[120:121], 0, v[72:73]
	s_add_i32 s33, s28, 0x80
	s_ashr_i32 s28, s33, 6
	s_and_b32 s28, s28, -4
	s_add_i32 s28, s28, s51
	s_ashr_i32 s29, s28, 31
	v_cmp_ne_u32_e32 vcc, 0, v237
	v_bfe_u32 v238, v68, 16, 1
	v_add3_u32 v68, v68, v238, s1
	v_bfe_u32 v238, v69, 16, 1
	v_add3_u32 v69, v69, v238, s1
	v_bfe_u32 v238, v70, 16, 1
	v_add3_u32 v70, v70, v238, s1
	v_bfe_u32 v238, v71, 16, 1
	v_add3_u32 v71, v71, v238, s1
	v_bfe_u32 v238, v64, 16, 1
	v_add3_u32 v64, v64, v238, s1
	v_bfe_u32 v238, v65, 16, 1
	v_add3_u32 v65, v65, v238, s1
	v_bfe_u32 v238, v66, 16, 1
	v_add3_u32 v66, v66, v238, s1
	v_bfe_u32 v238, v67, 16, 1
	v_add3_u32 v67, v67, v238, s1
	v_cndmask_b32_e32 v220, v68, v69, vcc
	v_cndmask_b32_e32 v224, v69, v68, vcc
	v_cndmask_b32_e32 v221, v70, v71, vcc
	v_cndmask_b32_e32 v225, v71, v70, vcc
	v_cndmask_b32_e32 v222, v64, v65, vcc
	v_cndmask_b32_e32 v226, v65, v64, vcc
	v_cndmask_b32_e32 v223, v66, v67, vcc
	v_cndmask_b32_e32 v227, v67, v66, vcc
	v_lshl_add_u64 v[228:229], v[72:73], 0, v[232:233]
	v_mov_b32_dpp v224, v224 quad_perm:[1,0,3,2] row_mask:0xf bank_mask:0xf
	v_mov_b32_dpp v225, v225 quad_perm:[1,0,3,2] row_mask:0xf bank_mask:0xf
	v_mov_b32_dpp v226, v226 quad_perm:[1,0,3,2] row_mask:0xf bank_mask:0xf
	v_mov_b32_dpp v227, v227 quad_perm:[1,0,3,2] row_mask:0xf bank_mask:0xf
	s_nop 0
	v_perm_b32 v220, v224, v220, v236
	v_perm_b32 v221, v225, v221, v236
	v_perm_b32 v222, v226, v222, v236
	v_perm_b32 v223, v227, v223, v236
	v_cmp_ne_u32_e32 vcc, 0, v239
	s_nop 1
	v_cndmask_b32_e32 v224, v221, v220, vcc
	v_cndmask_b32_e32 v225, v223, v222, vcc
	s_nop 0
	v_mov_b32_dpp v224, v224 quad_perm:[2,3,0,1] row_mask:0xf bank_mask:0xf
	v_mov_b32_dpp v225, v225 quad_perm:[2,3,0,1] row_mask:0xf bank_mask:0xf
	s_nop 0
	v_cndmask_b32_e32 v220, v220, v224, vcc
	v_cndmask_b32_e32 v221, v224, v221, vcc
	v_cndmask_b32_e32 v222, v222, v225, vcc
	v_cndmask_b32_e32 v223, v225, v223, vcc
	global_store_dwordx2 v[228:229], v[220:221], off
	global_store_dwordx2 v[228:229], v[222:223], off offset:2048
	v_or_b32_e32 v64, s33, v142
	s_lshl_b64 s[28:29], s[28:29], 16
	v_ashrrev_i32_e32 v65, 31, v64
	v_cvt_pk_bf16_f32 v60, v60, v61
	v_cvt_pk_bf16_f32 v61, v62, v63
	v_cvt_pk_bf16_f32 v62, v56, v57
	v_lshlrev_b64 v[56:57], 10, v[64:65]
	v_lshl_add_u64 v[56:57], s[14:15], 0, v[56:57]
	v_lshl_add_u64 v[56:57], v[56:57], 0, s[26:27]
	v_cvt_pk_bf16_f32 v63, v58, v59
	v_lshl_add_u64 v[56:57], v[56:57], 0, v[144:145]
	v_bitop3_b32 v58, s33, v184, v142 bitop3:0xc8
	flat_store_dwordx4 v[56:57], v[60:63]
	v_lshl_add_u64 v[56:57], v[136:137], 0, s[28:29]
	v_lshlrev_b32_e32 v58, 1, v58
	v_mov_b32_e32 v59, v145
	v_lshl_add_u64 v[58:59], v[56:57], 0, v[58:59]
	v_cmp_ne_u32_e32 vcc, 0, v237
	v_bfe_u32 v238, v52, 16, 1
	v_add3_u32 v52, v52, v238, s1
	v_bfe_u32 v238, v53, 16, 1
	v_add3_u32 v53, v53, v238, s1
	v_bfe_u32 v238, v54, 16, 1
	v_add3_u32 v54, v54, v238, s1
	v_bfe_u32 v238, v55, 16, 1
	v_add3_u32 v55, v55, v238, s1
	v_bfe_u32 v238, v48, 16, 1
	v_add3_u32 v48, v48, v238, s1
	v_bfe_u32 v238, v49, 16, 1
	v_add3_u32 v49, v49, v238, s1
	v_bfe_u32 v238, v50, 16, 1
	v_add3_u32 v50, v50, v238, s1
	v_bfe_u32 v238, v51, 16, 1
	v_add3_u32 v51, v51, v238, s1
	v_cndmask_b32_e32 v220, v52, v53, vcc
	v_cndmask_b32_e32 v224, v53, v52, vcc
	v_cndmask_b32_e32 v221, v54, v55, vcc
	v_cndmask_b32_e32 v225, v55, v54, vcc
	v_cndmask_b32_e32 v222, v48, v49, vcc
	v_cndmask_b32_e32 v226, v49, v48, vcc
	v_cndmask_b32_e32 v223, v50, v51, vcc
	v_cndmask_b32_e32 v227, v51, v50, vcc
	v_lshl_add_u64 v[228:229], v[58:59], 0, v[232:233]
	v_mov_b32_dpp v224, v224 quad_perm:[1,0,3,2] row_mask:0xf bank_mask:0xf
	v_mov_b32_dpp v225, v225 quad_perm:[1,0,3,2] row_mask:0xf bank_mask:0xf
	v_mov_b32_dpp v226, v226 quad_perm:[1,0,3,2] row_mask:0xf bank_mask:0xf
	v_mov_b32_dpp v227, v227 quad_perm:[1,0,3,2] row_mask:0xf bank_mask:0xf
	s_nop 0
	v_perm_b32 v220, v224, v220, v236
	v_perm_b32 v221, v225, v221, v236
	v_perm_b32 v222, v226, v222, v236
	v_perm_b32 v223, v227, v223, v236
	v_cmp_ne_u32_e32 vcc, 0, v239
	s_nop 1
	v_cndmask_b32_e32 v224, v221, v220, vcc
	v_cndmask_b32_e32 v225, v223, v222, vcc
	s_nop 0
	v_mov_b32_dpp v224, v224 quad_perm:[2,3,0,1] row_mask:0xf bank_mask:0xf
	v_mov_b32_dpp v225, v225 quad_perm:[2,3,0,1] row_mask:0xf bank_mask:0xf
	s_nop 0
	v_cndmask_b32_e32 v220, v220, v224, vcc
	v_cndmask_b32_e32 v221, v224, v221, vcc
	v_cndmask_b32_e32 v222, v222, v225, vcc
	v_cndmask_b32_e32 v223, v225, v223, vcc
	global_store_dwordx2 v[228:229], v[220:221], off
	global_store_dwordx2 v[228:229], v[222:223], off offset:2048
	v_or_b32_e32 v48, 16, v64
	v_ashrrev_i32_e32 v49, 31, v48
	v_cvt_pk_bf16_f32 v44, v44, v45
	v_cvt_pk_bf16_f32 v45, v46, v47
	v_cvt_pk_bf16_f32 v46, v40, v41
	v_lshlrev_b64 v[40:41], 10, v[48:49]
	v_lshl_add_u64 v[40:41], s[14:15], 0, v[40:41]
	v_lshl_add_u64 v[40:41], v[40:41], 0, s[26:27]
	v_cvt_pk_bf16_f32 v47, v42, v43
	v_lshl_add_u64 v[40:41], v[40:41], 0, v[144:145]
	flat_store_dwordx4 v[40:41], v[44:47]
	v_bitop3_b32 v40, v64, s56, 16 bitop3:0xc8
	v_lshlrev_b32_e32 v40, 1, v40
	v_mov_b32_e32 v41, v145
	v_lshl_add_u64 v[40:41], v[56:57], 0, v[40:41]
	v_cmp_ne_u32_e32 vcc, 0, v237
	v_bfe_u32 v238, v36, 16, 1
	v_add3_u32 v36, v36, v238, s1
	v_bfe_u32 v238, v37, 16, 1
	v_add3_u32 v37, v37, v238, s1
	v_bfe_u32 v238, v38, 16, 1
	v_add3_u32 v38, v38, v238, s1
	v_bfe_u32 v238, v39, 16, 1
	v_add3_u32 v39, v39, v238, s1
	v_bfe_u32 v238, v32, 16, 1
	v_add3_u32 v32, v32, v238, s1
	v_bfe_u32 v238, v33, 16, 1
	v_add3_u32 v33, v33, v238, s1
	v_bfe_u32 v238, v34, 16, 1
	v_add3_u32 v34, v34, v238, s1
	v_bfe_u32 v238, v35, 16, 1
	v_add3_u32 v35, v35, v238, s1
	v_cndmask_b32_e32 v220, v36, v37, vcc
	v_cndmask_b32_e32 v224, v37, v36, vcc
	v_cndmask_b32_e32 v221, v38, v39, vcc
	v_cndmask_b32_e32 v225, v39, v38, vcc
	v_cndmask_b32_e32 v222, v32, v33, vcc
	v_cndmask_b32_e32 v226, v33, v32, vcc
	v_cndmask_b32_e32 v223, v34, v35, vcc
	v_cndmask_b32_e32 v227, v35, v34, vcc
	v_lshl_add_u64 v[228:229], v[40:41], 0, v[232:233]
	v_mov_b32_dpp v224, v224 quad_perm:[1,0,3,2] row_mask:0xf bank_mask:0xf
	v_mov_b32_dpp v225, v225 quad_perm:[1,0,3,2] row_mask:0xf bank_mask:0xf
	v_mov_b32_dpp v226, v226 quad_perm:[1,0,3,2] row_mask:0xf bank_mask:0xf
	v_mov_b32_dpp v227, v227 quad_perm:[1,0,3,2] row_mask:0xf bank_mask:0xf
	s_nop 0
	v_perm_b32 v220, v224, v220, v236
	v_perm_b32 v221, v225, v221, v236
	v_perm_b32 v222, v226, v222, v236
	v_perm_b32 v223, v227, v223, v236
	v_cmp_ne_u32_e32 vcc, 0, v239
	s_nop 1
	v_cndmask_b32_e32 v224, v221, v220, vcc
	v_cndmask_b32_e32 v225, v223, v222, vcc
	s_nop 0
	v_mov_b32_dpp v224, v224 quad_perm:[2,3,0,1] row_mask:0xf bank_mask:0xf
	v_mov_b32_dpp v225, v225 quad_perm:[2,3,0,1] row_mask:0xf bank_mask:0xf
	s_nop 0
	v_cndmask_b32_e32 v220, v220, v224, vcc
	v_cndmask_b32_e32 v221, v224, v221, vcc
	v_cndmask_b32_e32 v222, v222, v225, vcc
	v_cndmask_b32_e32 v223, v225, v223, vcc
	global_store_dwordx2 v[228:229], v[220:221], off
	global_store_dwordx2 v[228:229], v[222:223], off offset:2048
	v_or_b32_e32 v32, 32, v64
	v_ashrrev_i32_e32 v33, 31, v32
	v_cvt_pk_bf16_f32 v28, v28, v29
	v_cvt_pk_bf16_f32 v29, v30, v31
	v_cvt_pk_bf16_f32 v30, v24, v25
	v_lshlrev_b64 v[24:25], 10, v[32:33]
	v_lshl_add_u64 v[24:25], s[14:15], 0, v[24:25]
	v_lshl_add_u64 v[24:25], v[24:25], 0, s[26:27]
	v_cvt_pk_bf16_f32 v31, v26, v27
	v_lshl_add_u64 v[24:25], v[24:25], 0, v[144:145]
	flat_store_dwordx4 v[24:25], v[28:31]
	v_bitop3_b32 v24, v64, s57, 32 bitop3:0xc8
	v_lshlrev_b32_e32 v24, 1, v24
	v_mov_b32_e32 v25, v145
	v_lshl_add_u64 v[24:25], v[56:57], 0, v[24:25]
	v_cmp_ne_u32_e32 vcc, 0, v237
	v_bfe_u32 v238, v20, 16, 1
	v_add3_u32 v20, v20, v238, s1
	v_bfe_u32 v238, v21, 16, 1
	v_add3_u32 v21, v21, v238, s1
	v_bfe_u32 v238, v22, 16, 1
	v_add3_u32 v22, v22, v238, s1
	v_bfe_u32 v238, v23, 16, 1
	v_add3_u32 v23, v23, v238, s1
	v_bfe_u32 v238, v16, 16, 1
	v_add3_u32 v16, v16, v238, s1
	v_bfe_u32 v238, v17, 16, 1
	v_add3_u32 v17, v17, v238, s1
	v_bfe_u32 v238, v18, 16, 1
	v_add3_u32 v18, v18, v238, s1
	v_bfe_u32 v238, v19, 16, 1
	v_add3_u32 v19, v19, v238, s1
	v_cndmask_b32_e32 v220, v20, v21, vcc
	v_cndmask_b32_e32 v224, v21, v20, vcc
	v_cndmask_b32_e32 v221, v22, v23, vcc
	v_cndmask_b32_e32 v225, v23, v22, vcc
	v_cndmask_b32_e32 v222, v16, v17, vcc
	v_cndmask_b32_e32 v226, v17, v16, vcc
	v_cndmask_b32_e32 v223, v18, v19, vcc
	v_cndmask_b32_e32 v227, v19, v18, vcc
	v_lshl_add_u64 v[228:229], v[24:25], 0, v[232:233]
	v_mov_b32_dpp v224, v224 quad_perm:[1,0,3,2] row_mask:0xf bank_mask:0xf
	v_mov_b32_dpp v225, v225 quad_perm:[1,0,3,2] row_mask:0xf bank_mask:0xf
	v_mov_b32_dpp v226, v226 quad_perm:[1,0,3,2] row_mask:0xf bank_mask:0xf
	v_mov_b32_dpp v227, v227 quad_perm:[1,0,3,2] row_mask:0xf bank_mask:0xf
	s_nop 0
	v_perm_b32 v220, v224, v220, v236
	v_perm_b32 v221, v225, v221, v236
	v_perm_b32 v222, v226, v222, v236
	v_perm_b32 v223, v227, v223, v236
	v_cmp_ne_u32_e32 vcc, 0, v239
	s_nop 1
	v_cndmask_b32_e32 v224, v221, v220, vcc
	v_cndmask_b32_e32 v225, v223, v222, vcc
	s_nop 0
	v_mov_b32_dpp v224, v224 quad_perm:[2,3,0,1] row_mask:0xf bank_mask:0xf
	v_mov_b32_dpp v225, v225 quad_perm:[2,3,0,1] row_mask:0xf bank_mask:0xf
	s_nop 0
	v_cndmask_b32_e32 v220, v220, v224, vcc
	v_cndmask_b32_e32 v221, v224, v221, vcc
	v_cndmask_b32_e32 v222, v222, v225, vcc
	v_cndmask_b32_e32 v223, v225, v223, vcc
	global_store_dwordx2 v[228:229], v[220:221], off
	global_store_dwordx2 v[228:229], v[222:223], off offset:2048
	v_or_b32_e32 v16, 48, v64
	v_ashrrev_i32_e32 v17, 31, v16
	v_cvt_pk_bf16_f32 v12, v12, v13
	v_cvt_pk_bf16_f32 v13, v14, v15
	v_cvt_pk_bf16_f32 v14, v8, v9
	v_lshlrev_b64 v[8:9], 10, v[16:17]
	v_lshl_add_u64 v[8:9], s[14:15], 0, v[8:9]
	v_lshl_add_u64 v[8:9], v[8:9], 0, s[26:27]
	v_cvt_pk_bf16_f32 v15, v10, v11
	v_lshl_add_u64 v[8:9], v[8:9], 0, v[144:145]
	flat_store_dwordx4 v[8:9], v[12:15]
	v_bitop3_b32 v8, v64, s53, 48 bitop3:0xc8
	v_lshlrev_b32_e32 v8, 1, v8
	v_mov_b32_e32 v9, v145
	v_lshl_add_u64 v[8:9], v[56:57], 0, v[8:9]
	v_cmp_ne_u32_e32 vcc, 0, v237
	v_bfe_u32 v238, v4, 16, 1
	v_add3_u32 v4, v4, v238, s1
	v_bfe_u32 v238, v5, 16, 1
	v_add3_u32 v5, v5, v238, s1
	v_bfe_u32 v238, v6, 16, 1
	v_add3_u32 v6, v6, v238, s1
	v_bfe_u32 v238, v7, 16, 1
	v_add3_u32 v7, v7, v238, s1
	v_bfe_u32 v238, v0, 16, 1
	v_add3_u32 v0, v0, v238, s1
	v_bfe_u32 v238, v1, 16, 1
	v_add3_u32 v1, v1, v238, s1
	v_bfe_u32 v238, v2, 16, 1
	v_add3_u32 v2, v2, v238, s1
	v_bfe_u32 v238, v3, 16, 1
	v_add3_u32 v3, v3, v238, s1
	v_cndmask_b32_e32 v220, v4, v5, vcc
	v_cndmask_b32_e32 v224, v5, v4, vcc
	v_cndmask_b32_e32 v221, v6, v7, vcc
	v_cndmask_b32_e32 v225, v7, v6, vcc
	v_cndmask_b32_e32 v222, v0, v1, vcc
	v_cndmask_b32_e32 v226, v1, v0, vcc
	v_cndmask_b32_e32 v223, v2, v3, vcc
	v_cndmask_b32_e32 v227, v3, v2, vcc
	v_lshl_add_u64 v[228:229], v[8:9], 0, v[232:233]
	v_mov_b32_dpp v224, v224 quad_perm:[1,0,3,2] row_mask:0xf bank_mask:0xf
	v_mov_b32_dpp v225, v225 quad_perm:[1,0,3,2] row_mask:0xf bank_mask:0xf
	v_mov_b32_dpp v226, v226 quad_perm:[1,0,3,2] row_mask:0xf bank_mask:0xf
	v_mov_b32_dpp v227, v227 quad_perm:[1,0,3,2] row_mask:0xf bank_mask:0xf
	s_nop 0
	v_perm_b32 v220, v224, v220, v236
	v_perm_b32 v221, v225, v221, v236
	v_perm_b32 v222, v226, v222, v236
	v_perm_b32 v223, v227, v223, v236
	v_cmp_ne_u32_e32 vcc, 0, v239
	s_nop 1
	v_cndmask_b32_e32 v224, v221, v220, vcc
	v_cndmask_b32_e32 v225, v223, v222, vcc
	s_nop 0
	v_mov_b32_dpp v224, v224 quad_perm:[2,3,0,1] row_mask:0xf bank_mask:0xf
	v_mov_b32_dpp v225, v225 quad_perm:[2,3,0,1] row_mask:0xf bank_mask:0xf
	s_nop 0
	v_cndmask_b32_e32 v220, v220, v224, vcc
	v_cndmask_b32_e32 v221, v224, v221, vcc
	v_cndmask_b32_e32 v222, v222, v225, vcc
	v_cndmask_b32_e32 v223, v225, v223, vcc
	global_store_dwordx2 v[228:229], v[220:221], off
	global_store_dwordx2 v[228:229], v[222:223], off offset:2048
	s_and_b64 vcc, exec, s[2:3]
	s_mov_b64 s[2:3], -1
	s_cbranch_vccnz .LBB0_1834
	s_andn2_b64 vcc, exec, s[12:13]
	s_cbranch_vccnz .LBB0_1833
	s_barrier
	s_branch .LBB0_1833
